# merge phase rewritten as one persistent software pipeline over all 80 k-steps per tile (branch+gate GEMMs chained, fragments double-buffered)
# speedup vs baseline: 1.0701x; 1.0294x over previous
.LBB0_79:
.LBB0_80:
	v_readlane_b32 s6, v239, 0
	v_readlane_b32 s7, v239, 1
	s_andn2_b64 vcc, exec, s[6:7]
	s_cbranch_vccnz .LBB0_90
	s_load_dwordx2 s[4:5], s[0:1], 0x130
	s_load_dwordx2 s[24:25], s[0:1], 0x108
	v_and_b32_e32 v0, 63, v133
	v_lshrrev_b32_e32 v131, 6, v133
	v_lshrrev_b32_e32 v195, 2, v0
	v_readfirstlane_b32 s15, v131
	v_lshlrev_b32_e32 v134, 11, v195
	v_lshlrev_b32_e32 v135, 9, v195
	v_and_b32_e32 v195, 3, v0
	v_lshlrev_b32_e32 v195, 4, v195
	v_lshrrev_b32_e32 v131, 5, v0
	v_lshlrev_b32_e32 v131, 5, v131
	v_xor_b32_e32 v195, v195, v131
	v_add_u32_e32 v134, v134, v195
	v_add_u32_e32 v135, v135, v195
	v_and_b32_e32 v195, 15, v0
	v_lshrrev_b32_e32 v131, 4, v0
	v_lshlrev_b32_e32 v141, 6, v195
	v_lshl_or_b32 v141, v131, 4, v141
	v_and_b32_e32 v143, 8, v0
	v_lshlrev_b32_e32 v143, 2, v143
	v_xor_b32_e32 v141, v141, v143
	v_lshlrev_b32_e32 v143, 11, v195
	v_lshl_or_b32 v143, v131, 3, v143
	v_lshlrev_b32_e32 v179, 4, v131
	s_waitcnt lgkmcnt(0)
	s_lshl_b32 s3, s62, 14
	s_add_u32 s24, s24, s3
	s_addc_u32 s25, s25, 0
	s_and_b32 s3, s15, 1
	s_lshl_b32 s3, s3, 13
	s_add_u32 s3, s3, 16384
	v_add_u32_e32 v142, s3, v141
	s_lshr_b32 s3, s15, 1
	s_lshl_b32 s3, s3, 13
	v_add_u32_e32 v141, s3, v141
	s_lshl_b32 s22, s15, 12
	s_mov_b32 s12, s79
	s_cmp_ge_u32 s12, 128
	s_cbranch_scc1 .Lgm_done
	s_lshr_b32 s3, s12, 6
	s_lshl_b32 s3, s3, 3
	s_add_u32 s3, s3, s65
	s_lshl_b32 s3, s3, 3
	s_bfe_u32 s17, s12, 0x30003
	s_add_u32 s13, s3, s17
	s_and_b32 s14, s12, 7
	s_lshl_b32 s13, s13, 7
	s_lshl_b32 s14, s14, 7
	s_lshl_b32 s3, s15, 5
	s_add_u32 s17, s3, s13
	s_lshl_b32 s17, s17, 11
	s_add_u32 s17, s17, 0x9c27800
	s_add_u32 s6, s4, s17
	s_addc_u32 s7, s5, 0
	s_add_u32 s17, s3, s14
	s_lshl_b32 s17, s17, 9
	s_add_u32 s17, s17, 0x1727800
	s_add_u32 s8, s4, s17
	s_addc_u32 s9, s5, 0
	s_barrier
	v_mov_b32_e32 v136, v134
	v_mov_b32_e32 v137, v135
	s_add_u32 m0, s22, 0x0
	v_mov_b32_e32 v177, v136
	global_load_lds_dwordx4 v177, s[6:7]
	s_add_u32 m0, s22, 0x400
	v_add_u32_e32 v178, 0x40, v136
	global_load_lds_dwordx4 v178, s[6:7]
	s_add_u32 m0, s22, 0x800
	v_add_u32_e32 v177, 0x8000, v136
	global_load_lds_dwordx4 v177, s[6:7]
	s_add_u32 m0, s22, 0xc00
	v_add_u32_e32 v178, 0x8040, v136
	global_load_lds_dwordx4 v178, s[6:7]
	s_add_u32 m0, s22, 0x4000
	v_mov_b32_e32 v177, v137
	global_load_lds_dwordx4 v177, s[8:9]
	s_add_u32 m0, s22, 0x4400
	v_add_u32_e32 v178, 0x40, v137
	global_load_lds_dwordx4 v178, s[8:9]
	s_add_u32 m0, s22, 0x4800
	v_add_u32_e32 v177, 0x2000, v137
	global_load_lds_dwordx4 v177, s[8:9]
	s_add_u32 m0, s22, 0x4c00
	v_add_u32_e32 v178, 0x2040, v137
	global_load_lds_dwordx4 v178, s[8:9]
	v_add_u32_e32 v136, 0x80, v136
	v_add_u32_e32 v137, 0x80, v137
	s_add_u32 m0, s22, 0x8000
	v_mov_b32_e32 v177, v136
	global_load_lds_dwordx4 v177, s[6:7]
	s_add_u32 m0, s22, 0x8400
	v_add_u32_e32 v178, 0x40, v136
	global_load_lds_dwordx4 v178, s[6:7]
	s_add_u32 m0, s22, 0x8800
	v_add_u32_e32 v177, 0x8000, v136
	global_load_lds_dwordx4 v177, s[6:7]
	s_add_u32 m0, s22, 0x8c00
	v_add_u32_e32 v178, 0x8040, v136
	global_load_lds_dwordx4 v178, s[6:7]
	s_add_u32 m0, s22, 0xc000
	v_mov_b32_e32 v177, v137
	global_load_lds_dwordx4 v177, s[8:9]
	s_add_u32 m0, s22, 0xc400
	v_add_u32_e32 v178, 0x40, v137
	global_load_lds_dwordx4 v178, s[8:9]
	s_add_u32 m0, s22, 0xc800
	v_add_u32_e32 v177, 0x2000, v137
	global_load_lds_dwordx4 v177, s[8:9]
	s_add_u32 m0, s22, 0xcc00
	v_add_u32_e32 v178, 0x2040, v137
	global_load_lds_dwordx4 v178, s[8:9]
	v_add_u32_e32 v136, 0x80, v136
	v_add_u32_e32 v137, 0x80, v137
	s_waitcnt vmcnt(0)
	s_barrier
	ds_read_b128 v[90:93], v142
	ds_read_b128 v[94:97], v142 offset:2048
	ds_read_b128 v[98:101], v142 offset:4096
	ds_read_b128 v[102:105], v142 offset:6144
	ds_read_b128 v[106:109], v141
	ds_read_b128 v[110:113], v141 offset:2048
	ds_read_b128 v[114:117], v141 offset:4096
	ds_read_b128 v[118:121], v141 offset:6144
.Lgm_tile:
	s_lshl_b32 s3, s15, 5
	s_add_u32 s17, s3, s13
	s_lshl_b32 s17, s17, 11
	s_add_u32 s17, s17, 0x2b27800
	s_add_u32 s18, s4, s17
	s_addc_u32 s19, s5, 0
	s_add_u32 s17, s3, s14
	s_lshl_b32 s17, s17, 11
	s_add_u32 s17, s17, 0xf27800
	s_add_u32 s20, s4, s17
	s_addc_u32 s21, s5, 0
	s_lshr_b32 s3, s15, 1
	s_lshl_b32 s3, s3, 6
	s_add_u32 s3, s3, s13
	s_lshl_b32 s17, s3, 11
	s_and_b32 s3, s15, 1
	s_lshl_b32 s3, s3, 6
	s_add_u32 s3, s3, s14
	s_lshl_b32 s23, s3, 1
	s_add_u32 s17, s17, s23
	s_add_u32 s17, s17, 0x4b27800
	s_add_u32 s10, s4, s17
	s_addc_u32 s11, s5, 0
	s_lshl_b32 s3, s3, 2
	v_add_u32_e32 v176, s3, v179
	v_mov_b32_e32 v140, v134
	v_mov_b32_e32 v66, 0
	v_mov_b32_e32 v67, 0
	v_mov_b32_e32 v68, 0
	v_mov_b32_e32 v69, 0
	v_mov_b32_e32 v70, 0
	v_mov_b32_e32 v71, 0
	v_mov_b32_e32 v72, 0
	v_mov_b32_e32 v73, 0
	v_mov_b32_e32 v74, 0
	v_mov_b32_e32 v75, 0
	v_mov_b32_e32 v76, 0
	v_mov_b32_e32 v77, 0
	v_mov_b32_e32 v78, 0
	v_mov_b32_e32 v79, 0
	v_mov_b32_e32 v80, 0
	v_mov_b32_e32 v81, 0
	v_mov_b32_e32 v82, 0
	v_mov_b32_e32 v83, 0
	v_mov_b32_e32 v84, 0
	v_mov_b32_e32 v85, 0
	v_mov_b32_e32 v86, 0
	v_mov_b32_e32 v87, 0
	v_mov_b32_e32 v88, 0
	v_mov_b32_e32 v89, 0
	v_mov_b32_e32 v122, 0
	v_mov_b32_e32 v123, 0
	v_mov_b32_e32 v124, 0
	v_mov_b32_e32 v125, 0
	v_mov_b32_e32 v126, 0
	v_mov_b32_e32 v127, 0
	v_mov_b32_e32 v128, 0
	v_mov_b32_e32 v129, 0
	s_mov_b32 s26, 0
.Lgm_branch:
	s_waitcnt lgkmcnt(0)
	v_mfma_f32_16x16x32_bf16 v[2:5], v[90:93], v[106:109], 0
	ds_read_b128 v[144:147], v142 offset:1024
	v_mfma_f32_16x16x32_bf16 v[6:9], v[94:97], v[106:109], 0
	ds_read_b128 v[148:151], v142 offset:3072
	v_mfma_f32_16x16x32_bf16 v[10:13], v[98:101], v[106:109], 0
	ds_read_b128 v[152:155], v142 offset:5120
	v_mfma_f32_16x16x32_bf16 v[14:17], v[102:105], v[106:109], 0
	ds_read_b128 v[156:159], v142 offset:7168
	v_mfma_f32_16x16x32_bf16 v[18:21], v[90:93], v[110:113], 0
	ds_read_b128 v[160:163], v141 offset:1024
	v_mfma_f32_16x16x32_bf16 v[22:25], v[94:97], v[110:113], 0
	ds_read_b128 v[164:167], v141 offset:3072
	v_mfma_f32_16x16x32_bf16 v[26:29], v[98:101], v[110:113], 0
	ds_read_b128 v[168:171], v141 offset:5120
	v_mfma_f32_16x16x32_bf16 v[30:33], v[102:105], v[110:113], 0
	ds_read_b128 v[172:175], v141 offset:7168
	v_mfma_f32_16x16x32_bf16 v[34:37], v[90:93], v[114:117], 0
	v_mfma_f32_16x16x32_bf16 v[38:41], v[94:97], v[114:117], 0
	v_mfma_f32_16x16x32_bf16 v[42:45], v[98:101], v[114:117], 0
	v_mfma_f32_16x16x32_bf16 v[46:49], v[102:105], v[114:117], 0
	v_mfma_f32_16x16x32_bf16 v[50:53], v[90:93], v[118:121], 0
	v_mfma_f32_16x16x32_bf16 v[54:57], v[94:97], v[118:121], 0
	v_mfma_f32_16x16x32_bf16 v[58:61], v[98:101], v[118:121], 0
	v_mfma_f32_16x16x32_bf16 v[62:65], v[102:105], v[118:121], 0
	s_waitcnt vmcnt(0) lgkmcnt(0)
	s_barrier
	v_mfma_f32_16x16x32_bf16 v[2:5], v[144:147], v[160:163], v[2:5]
	ds_read_b128 v[90:93], v142 offset:32768
	s_add_u32 m0, s22, 0x0
	v_mov_b32_e32 v177, v136
	global_load_lds_dwordx4 v177, s[6:7]
	v_mfma_f32_16x16x32_bf16 v[6:9], v[148:151], v[160:163], v[6:9]
	ds_read_b128 v[94:97], v142 offset:34816
	s_add_u32 m0, s22, 0x400
	v_add_u32_e32 v178, 0x40, v136
	global_load_lds_dwordx4 v178, s[6:7]
	v_mfma_f32_16x16x32_bf16 v[10:13], v[152:155], v[160:163], v[10:13]
	ds_read_b128 v[98:101], v142 offset:36864
	s_add_u32 m0, s22, 0x800
	v_add_u32_e32 v177, 0x8000, v136
	global_load_lds_dwordx4 v177, s[6:7]
	v_mfma_f32_16x16x32_bf16 v[14:17], v[156:159], v[160:163], v[14:17]
	ds_read_b128 v[102:105], v142 offset:38912
	s_add_u32 m0, s22, 0xc00
	v_add_u32_e32 v178, 0x8040, v136
	global_load_lds_dwordx4 v178, s[6:7]
	v_mfma_f32_16x16x32_bf16 v[18:21], v[144:147], v[164:167], v[18:21]
	ds_read_b128 v[106:109], v141 offset:32768
	s_add_u32 m0, s22, 0x4000
	v_mov_b32_e32 v177, v137
	global_load_lds_dwordx4 v177, s[8:9]
	v_mfma_f32_16x16x32_bf16 v[22:25], v[148:151], v[164:167], v[22:25]
	ds_read_b128 v[110:113], v141 offset:34816
	s_add_u32 m0, s22, 0x4400
	v_add_u32_e32 v178, 0x40, v137
	global_load_lds_dwordx4 v178, s[8:9]
	v_mfma_f32_16x16x32_bf16 v[26:29], v[152:155], v[164:167], v[26:29]
	ds_read_b128 v[114:117], v141 offset:36864
	s_add_u32 m0, s22, 0x4800
	v_add_u32_e32 v177, 0x2000, v137
	global_load_lds_dwordx4 v177, s[8:9]
	v_mfma_f32_16x16x32_bf16 v[30:33], v[156:159], v[164:167], v[30:33]
	ds_read_b128 v[118:121], v141 offset:38912
	s_add_u32 m0, s22, 0x4c00
	v_add_u32_e32 v178, 0x2040, v137
	global_load_lds_dwordx4 v178, s[8:9]
	v_mfma_f32_16x16x32_bf16 v[34:37], v[144:147], v[168:171], v[34:37]
	v_mfma_f32_16x16x32_bf16 v[38:41], v[148:151], v[168:171], v[38:41]
	v_mfma_f32_16x16x32_bf16 v[42:45], v[152:155], v[168:171], v[42:45]
	v_mfma_f32_16x16x32_bf16 v[46:49], v[156:159], v[168:171], v[46:49]
	v_mfma_f32_16x16x32_bf16 v[50:53], v[144:147], v[172:175], v[50:53]
	v_mfma_f32_16x16x32_bf16 v[54:57], v[148:151], v[172:175], v[54:57]
	v_mfma_f32_16x16x32_bf16 v[58:61], v[152:155], v[172:175], v[58:61]
	v_mfma_f32_16x16x32_bf16 v[62:65], v[156:159], v[172:175], v[62:65]
	v_add_u32_e32 v136, 0x80, v136
	v_add_u32_e32 v137, 0x80, v137
	s_waitcnt lgkmcnt(0)
	v_mfma_f32_16x16x32_bf16 v[2:5], v[90:93], v[106:109], v[2:5]
	ds_read_b128 v[144:147], v142 offset:33792
	v_mfma_f32_16x16x32_bf16 v[6:9], v[94:97], v[106:109], v[6:9]
	ds_read_b128 v[148:151], v142 offset:35840
	v_mfma_f32_16x16x32_bf16 v[10:13], v[98:101], v[106:109], v[10:13]
	ds_read_b128 v[152:155], v142 offset:37888
	v_mfma_f32_16x16x32_bf16 v[14:17], v[102:105], v[106:109], v[14:17]
	ds_read_b128 v[156:159], v142 offset:39936
	v_mfma_f32_16x16x32_bf16 v[18:21], v[90:93], v[110:113], v[18:21]
	ds_read_b128 v[160:163], v141 offset:33792
	v_mfma_f32_16x16x32_bf16 v[22:25], v[94:97], v[110:113], v[22:25]
	ds_read_b128 v[164:167], v141 offset:35840
	v_mfma_f32_16x16x32_bf16 v[26:29], v[98:101], v[110:113], v[26:29]
	ds_read_b128 v[168:171], v141 offset:37888
	v_mfma_f32_16x16x32_bf16 v[30:33], v[102:105], v[110:113], v[30:33]
	ds_read_b128 v[172:175], v141 offset:39936
	v_mfma_f32_16x16x32_bf16 v[34:37], v[90:93], v[114:117], v[34:37]
	v_mfma_f32_16x16x32_bf16 v[38:41], v[94:97], v[114:117], v[38:41]
	v_mfma_f32_16x16x32_bf16 v[42:45], v[98:101], v[114:117], v[42:45]
	v_mfma_f32_16x16x32_bf16 v[46:49], v[102:105], v[114:117], v[46:49]
	v_mfma_f32_16x16x32_bf16 v[50:53], v[90:93], v[118:121], v[50:53]
	v_mfma_f32_16x16x32_bf16 v[54:57], v[94:97], v[118:121], v[54:57]
	v_mfma_f32_16x16x32_bf16 v[58:61], v[98:101], v[118:121], v[58:61]
	v_mfma_f32_16x16x32_bf16 v[62:65], v[102:105], v[118:121], v[62:65]
	s_waitcnt vmcnt(0) lgkmcnt(0)
	s_barrier
	v_mfma_f32_16x16x32_bf16 v[2:5], v[144:147], v[160:163], v[2:5]
	ds_read_b128 v[90:93], v142
	s_add_u32 m0, s22, 0x8000
	v_mov_b32_e32 v177, v136
	global_load_lds_dwordx4 v177, s[6:7]
	v_mfma_f32_16x16x32_bf16 v[6:9], v[148:151], v[160:163], v[6:9]
	ds_read_b128 v[94:97], v142 offset:2048
	s_add_u32 m0, s22, 0x8400
	v_add_u32_e32 v178, 0x40, v136
	global_load_lds_dwordx4 v178, s[6:7]
	v_mfma_f32_16x16x32_bf16 v[10:13], v[152:155], v[160:163], v[10:13]
	ds_read_b128 v[98:101], v142 offset:4096
	s_add_u32 m0, s22, 0x8800
	v_add_u32_e32 v177, 0x8000, v136
	global_load_lds_dwordx4 v177, s[6:7]
	v_mfma_f32_16x16x32_bf16 v[14:17], v[156:159], v[160:163], v[14:17]
	ds_read_b128 v[102:105], v142 offset:6144
	s_add_u32 m0, s22, 0x8c00
	v_add_u32_e32 v178, 0x8040, v136
	global_load_lds_dwordx4 v178, s[6:7]
	v_mfma_f32_16x16x32_bf16 v[18:21], v[144:147], v[164:167], v[18:21]
	ds_read_b128 v[106:109], v141
	s_add_u32 m0, s22, 0xc000
	v_mov_b32_e32 v177, v137
	global_load_lds_dwordx4 v177, s[8:9]
	v_mfma_f32_16x16x32_bf16 v[22:25], v[148:151], v[164:167], v[22:25]
	ds_read_b128 v[110:113], v141 offset:2048
	s_add_u32 m0, s22, 0xc400
	v_add_u32_e32 v178, 0x40, v137
	global_load_lds_dwordx4 v178, s[8:9]
	v_mfma_f32_16x16x32_bf16 v[26:29], v[152:155], v[164:167], v[26:29]
	ds_read_b128 v[114:117], v141 offset:4096
	s_add_u32 m0, s22, 0xc800
	v_add_u32_e32 v177, 0x2000, v137
	global_load_lds_dwordx4 v177, s[8:9]
	v_mfma_f32_16x16x32_bf16 v[30:33], v[156:159], v[164:167], v[30:33]
	ds_read_b128 v[118:121], v141 offset:6144
	s_add_u32 m0, s22, 0xcc00
	v_add_u32_e32 v178, 0x2040, v137
	global_load_lds_dwordx4 v178, s[8:9]
	v_mfma_f32_16x16x32_bf16 v[34:37], v[144:147], v[168:171], v[34:37]
	v_mfma_f32_16x16x32_bf16 v[38:41], v[148:151], v[168:171], v[38:41]
	v_mfma_f32_16x16x32_bf16 v[42:45], v[152:155], v[168:171], v[42:45]
	v_mfma_f32_16x16x32_bf16 v[46:49], v[156:159], v[168:171], v[46:49]
	v_mfma_f32_16x16x32_bf16 v[50:53], v[144:147], v[172:175], v[50:53]
	v_mfma_f32_16x16x32_bf16 v[54:57], v[148:151], v[172:175], v[54:57]
	v_mfma_f32_16x16x32_bf16 v[58:61], v[152:155], v[172:175], v[58:61]
	v_mfma_f32_16x16x32_bf16 v[62:65], v[156:159], v[172:175], v[62:65]
	v_add_u32_e32 v136, 0x80, v136
	v_add_u32_e32 v137, 0x80, v137
	v_mov_b32_e32 v138, v134
	v_mov_b32_e32 v139, v140
	v_add_u32_e32 v140, 0x200000, v140
	s_waitcnt lgkmcnt(0)
	v_mfma_f32_16x16x32_bf16 v[2:5], v[90:93], v[106:109], v[2:5]
	ds_read_b128 v[144:147], v142 offset:1024
	v_mfma_f32_16x16x32_bf16 v[6:9], v[94:97], v[106:109], v[6:9]
	ds_read_b128 v[148:151], v142 offset:3072
	v_mfma_f32_16x16x32_bf16 v[10:13], v[98:101], v[106:109], v[10:13]
	ds_read_b128 v[152:155], v142 offset:5120
	v_mfma_f32_16x16x32_bf16 v[14:17], v[102:105], v[106:109], v[14:17]
	ds_read_b128 v[156:159], v142 offset:7168
	v_mfma_f32_16x16x32_bf16 v[18:21], v[90:93], v[110:113], v[18:21]
	ds_read_b128 v[160:163], v141 offset:1024
	v_mfma_f32_16x16x32_bf16 v[22:25], v[94:97], v[110:113], v[22:25]
	ds_read_b128 v[164:167], v141 offset:3072
	v_mfma_f32_16x16x32_bf16 v[26:29], v[98:101], v[110:113], v[26:29]
	ds_read_b128 v[168:171], v141 offset:5120
	v_mfma_f32_16x16x32_bf16 v[30:33], v[102:105], v[110:113], v[30:33]
	ds_read_b128 v[172:175], v141 offset:7168
	v_mfma_f32_16x16x32_bf16 v[34:37], v[90:93], v[114:117], v[34:37]
	v_mfma_f32_16x16x32_bf16 v[38:41], v[94:97], v[114:117], v[38:41]
	v_mfma_f32_16x16x32_bf16 v[42:45], v[98:101], v[114:117], v[42:45]
	v_mfma_f32_16x16x32_bf16 v[46:49], v[102:105], v[114:117], v[46:49]
	v_mfma_f32_16x16x32_bf16 v[50:53], v[90:93], v[118:121], v[50:53]
	v_mfma_f32_16x16x32_bf16 v[54:57], v[94:97], v[118:121], v[54:57]
	v_mfma_f32_16x16x32_bf16 v[58:61], v[98:101], v[118:121], v[58:61]
	v_mfma_f32_16x16x32_bf16 v[62:65], v[102:105], v[118:121], v[62:65]
	s_waitcnt vmcnt(0) lgkmcnt(0)
	s_barrier
	v_mfma_f32_16x16x32_bf16 v[2:5], v[144:147], v[160:163], v[2:5]
	ds_read_b128 v[90:93], v142 offset:32768
	s_add_u32 m0, s22, 0x0
	v_mov_b32_e32 v177, v138
	global_load_lds_dwordx4 v177, s[18:19]
	v_mfma_f32_16x16x32_bf16 v[6:9], v[148:151], v[160:163], v[6:9]
	ds_read_b128 v[94:97], v142 offset:34816
	s_add_u32 m0, s22, 0x400
	v_add_u32_e32 v178, 0x40, v138
	global_load_lds_dwordx4 v178, s[18:19]
	v_mfma_f32_16x16x32_bf16 v[10:13], v[152:155], v[160:163], v[10:13]
	ds_read_b128 v[98:101], v142 offset:36864
	s_add_u32 m0, s22, 0x800
	v_add_u32_e32 v177, 0x8000, v138
	global_load_lds_dwordx4 v177, s[18:19]
	v_mfma_f32_16x16x32_bf16 v[14:17], v[156:159], v[160:163], v[14:17]
	ds_read_b128 v[102:105], v142 offset:38912
	s_add_u32 m0, s22, 0xc00
	v_add_u32_e32 v178, 0x8040, v138
	global_load_lds_dwordx4 v178, s[18:19]
	v_mfma_f32_16x16x32_bf16 v[18:21], v[144:147], v[164:167], v[18:21]
	ds_read_b128 v[106:109], v141 offset:32768
	s_add_u32 m0, s22, 0x4000
	v_mov_b32_e32 v177, v139
	global_load_lds_dwordx4 v177, s[20:21]
	v_mfma_f32_16x16x32_bf16 v[22:25], v[148:151], v[164:167], v[22:25]
	ds_read_b128 v[110:113], v141 offset:34816
	s_add_u32 m0, s22, 0x4400
	v_add_u32_e32 v178, 0x40, v139
	global_load_lds_dwordx4 v178, s[20:21]
	v_mfma_f32_16x16x32_bf16 v[26:29], v[152:155], v[164:167], v[26:29]
	ds_read_b128 v[114:117], v141 offset:36864
	s_add_u32 m0, s22, 0x4800
	v_add_u32_e32 v177, 0x8000, v139
	global_load_lds_dwordx4 v177, s[20:21]
	v_mfma_f32_16x16x32_bf16 v[30:33], v[156:159], v[164:167], v[30:33]
	ds_read_b128 v[118:121], v141 offset:38912
	s_add_u32 m0, s22, 0x4c00
	v_add_u32_e32 v178, 0x8040, v139
	global_load_lds_dwordx4 v178, s[20:21]
	v_mfma_f32_16x16x32_bf16 v[34:37], v[144:147], v[168:171], v[34:37]
	v_mfma_f32_16x16x32_bf16 v[38:41], v[148:151], v[168:171], v[38:41]
	v_mfma_f32_16x16x32_bf16 v[42:45], v[152:155], v[168:171], v[42:45]
	v_mfma_f32_16x16x32_bf16 v[46:49], v[156:159], v[168:171], v[46:49]
	v_mfma_f32_16x16x32_bf16 v[50:53], v[144:147], v[172:175], v[50:53]
	v_mfma_f32_16x16x32_bf16 v[54:57], v[148:151], v[172:175], v[54:57]
	v_mfma_f32_16x16x32_bf16 v[58:61], v[152:155], v[172:175], v[58:61]
	v_mfma_f32_16x16x32_bf16 v[62:65], v[156:159], v[172:175], v[62:65]
	v_add_u32_e32 v138, 0x80, v138
	v_add_u32_e32 v139, 0x80, v139
	s_waitcnt lgkmcnt(0)
	v_mfma_f32_16x16x32_bf16 v[2:5], v[90:93], v[106:109], v[2:5]
	ds_read_b128 v[144:147], v142 offset:33792
	v_mfma_f32_16x16x32_bf16 v[6:9], v[94:97], v[106:109], v[6:9]
	ds_read_b128 v[148:151], v142 offset:35840
	v_mfma_f32_16x16x32_bf16 v[10:13], v[98:101], v[106:109], v[10:13]
	ds_read_b128 v[152:155], v142 offset:37888
	v_mfma_f32_16x16x32_bf16 v[14:17], v[102:105], v[106:109], v[14:17]
	ds_read_b128 v[156:159], v142 offset:39936
	v_mfma_f32_16x16x32_bf16 v[18:21], v[90:93], v[110:113], v[18:21]
	ds_read_b128 v[160:163], v141 offset:33792
	v_mfma_f32_16x16x32_bf16 v[22:25], v[94:97], v[110:113], v[22:25]
	ds_read_b128 v[164:167], v141 offset:35840
	v_mfma_f32_16x16x32_bf16 v[26:29], v[98:101], v[110:113], v[26:29]
	ds_read_b128 v[168:171], v141 offset:37888
	v_mfma_f32_16x16x32_bf16 v[30:33], v[102:105], v[110:113], v[30:33]
	ds_read_b128 v[172:175], v141 offset:39936
	v_mfma_f32_16x16x32_bf16 v[34:37], v[90:93], v[114:117], v[34:37]
	v_mfma_f32_16x16x32_bf16 v[38:41], v[94:97], v[114:117], v[38:41]
	v_mfma_f32_16x16x32_bf16 v[42:45], v[98:101], v[114:117], v[42:45]
	v_mfma_f32_16x16x32_bf16 v[46:49], v[102:105], v[114:117], v[46:49]
	v_mfma_f32_16x16x32_bf16 v[50:53], v[90:93], v[118:121], v[50:53]
	v_mfma_f32_16x16x32_bf16 v[54:57], v[94:97], v[118:121], v[54:57]
	v_mfma_f32_16x16x32_bf16 v[58:61], v[98:101], v[118:121], v[58:61]
	v_mfma_f32_16x16x32_bf16 v[62:65], v[102:105], v[118:121], v[62:65]
	s_waitcnt vmcnt(0) lgkmcnt(0)
	s_barrier
	v_mfma_f32_16x16x32_bf16 v[2:5], v[144:147], v[160:163], v[2:5]
	ds_read_b128 v[90:93], v142
	s_add_u32 m0, s22, 0x8000
	v_mov_b32_e32 v177, v138
	global_load_lds_dwordx4 v177, s[18:19]
	v_mfma_f32_16x16x32_bf16 v[6:9], v[148:151], v[160:163], v[6:9]
	ds_read_b128 v[94:97], v142 offset:2048
	s_add_u32 m0, s22, 0x8400
	v_add_u32_e32 v178, 0x40, v138
	global_load_lds_dwordx4 v178, s[18:19]
	v_mfma_f32_16x16x32_bf16 v[10:13], v[152:155], v[160:163], v[10:13]
	ds_read_b128 v[98:101], v142 offset:4096
	s_add_u32 m0, s22, 0x8800
	v_add_u32_e32 v177, 0x8000, v138
	global_load_lds_dwordx4 v177, s[18:19]
	v_mfma_f32_16x16x32_bf16 v[14:17], v[156:159], v[160:163], v[14:17]
	ds_read_b128 v[102:105], v142 offset:6144
	s_add_u32 m0, s22, 0x8c00
	v_add_u32_e32 v178, 0x8040, v138
	global_load_lds_dwordx4 v178, s[18:19]
	v_mfma_f32_16x16x32_bf16 v[18:21], v[144:147], v[164:167], v[18:21]
	ds_read_b128 v[106:109], v141
	s_add_u32 m0, s22, 0xc000
	v_mov_b32_e32 v177, v139
	global_load_lds_dwordx4 v177, s[20:21]
	v_mfma_f32_16x16x32_bf16 v[22:25], v[148:151], v[164:167], v[22:25]
	ds_read_b128 v[110:113], v141 offset:2048
	s_add_u32 m0, s22, 0xc400
	v_add_u32_e32 v178, 0x40, v139
	global_load_lds_dwordx4 v178, s[20:21]
	v_mfma_f32_16x16x32_bf16 v[26:29], v[152:155], v[164:167], v[26:29]
	ds_read_b128 v[114:117], v141 offset:4096
	s_add_u32 m0, s22, 0xc800
	v_add_u32_e32 v177, 0x8000, v139
	global_load_lds_dwordx4 v177, s[20:21]
	v_mfma_f32_16x16x32_bf16 v[30:33], v[156:159], v[164:167], v[30:33]
	ds_read_b128 v[118:121], v141 offset:6144
	s_add_u32 m0, s22, 0xcc00
	v_add_u32_e32 v178, 0x8040, v139
	global_load_lds_dwordx4 v178, s[20:21]
	v_mfma_f32_16x16x32_bf16 v[34:37], v[144:147], v[168:171], v[34:37]
	v_mfma_f32_16x16x32_bf16 v[38:41], v[148:151], v[168:171], v[38:41]
	v_mfma_f32_16x16x32_bf16 v[42:45], v[152:155], v[168:171], v[42:45]
	v_mfma_f32_16x16x32_bf16 v[46:49], v[156:159], v[168:171], v[46:49]
	v_mfma_f32_16x16x32_bf16 v[50:53], v[144:147], v[172:175], v[50:53]
	v_mfma_f32_16x16x32_bf16 v[54:57], v[148:151], v[172:175], v[54:57]
	v_mfma_f32_16x16x32_bf16 v[58:61], v[152:155], v[172:175], v[58:61]
	v_mfma_f32_16x16x32_bf16 v[62:65], v[156:159], v[172:175], v[62:65]
	v_add_u32_e32 v138, 0x80, v138
	v_add_u32_e32 v139, 0x80, v139
	v_cvt_pk_bf16_f32 v196, v2, v3
	v_cvt_pk_bf16_f32 v197, v4, v5
	v_cvt_pk_bf16_f32 v198, v6, v7
	v_cvt_pk_bf16_f32 v199, v8, v9
	v_cvt_pk_bf16_f32 v200, v10, v11
	v_cvt_pk_bf16_f32 v201, v12, v13
	v_cvt_pk_bf16_f32 v202, v14, v15
	v_cvt_pk_bf16_f32 v203, v16, v17
	v_cvt_pk_bf16_f32 v204, v18, v19
	v_cvt_pk_bf16_f32 v205, v20, v21
	v_cvt_pk_bf16_f32 v206, v22, v23
	v_cvt_pk_bf16_f32 v207, v24, v25
	v_cvt_pk_bf16_f32 v212, v26, v27
	v_cvt_pk_bf16_f32 v213, v28, v29
	v_cvt_pk_bf16_f32 v214, v30, v31
	v_cvt_pk_bf16_f32 v215, v32, v33
	v_cvt_pk_bf16_f32 v216, v34, v35
	v_cvt_pk_bf16_f32 v217, v36, v37
	v_cvt_pk_bf16_f32 v218, v38, v39
	v_cvt_pk_bf16_f32 v219, v40, v41
	v_cvt_pk_bf16_f32 v220, v42, v43
	v_cvt_pk_bf16_f32 v221, v44, v45
	v_cvt_pk_bf16_f32 v222, v46, v47
	v_cvt_pk_bf16_f32 v223, v48, v49
	v_cvt_pk_bf16_f32 v224, v50, v51
	v_cvt_pk_bf16_f32 v225, v52, v53
	v_cvt_pk_bf16_f32 v226, v54, v55
	v_cvt_pk_bf16_f32 v227, v56, v57
	v_cvt_pk_bf16_f32 v228, v58, v59
	v_cvt_pk_bf16_f32 v229, v60, v61
	v_cvt_pk_bf16_f32 v230, v62, v63
	v_cvt_pk_bf16_f32 v231, v64, v65
	s_waitcnt lgkmcnt(0)
	v_mfma_f32_16x16x32_bf16 v[2:5], v[90:93], v[106:109], 0
	ds_read_b128 v[144:147], v142 offset:1024
	v_mfma_f32_16x16x32_bf16 v[6:9], v[94:97], v[106:109], 0
	ds_read_b128 v[148:151], v142 offset:3072
	v_mfma_f32_16x16x32_bf16 v[10:13], v[98:101], v[106:109], 0
	ds_read_b128 v[152:155], v142 offset:5120
	v_mfma_f32_16x16x32_bf16 v[14:17], v[102:105], v[106:109], 0
	ds_read_b128 v[156:159], v142 offset:7168
	v_mfma_f32_16x16x32_bf16 v[18:21], v[90:93], v[110:113], 0
	ds_read_b128 v[160:163], v141 offset:1024
	v_mfma_f32_16x16x32_bf16 v[22:25], v[94:97], v[110:113], 0
	ds_read_b128 v[164:167], v141 offset:3072
	v_mfma_f32_16x16x32_bf16 v[26:29], v[98:101], v[110:113], 0
	ds_read_b128 v[168:171], v141 offset:5120
	v_mfma_f32_16x16x32_bf16 v[30:33], v[102:105], v[110:113], 0
	ds_read_b128 v[172:175], v141 offset:7168
	v_mfma_f32_16x16x32_bf16 v[34:37], v[90:93], v[114:117], 0
	v_mfma_f32_16x16x32_bf16 v[38:41], v[94:97], v[114:117], 0
	v_mfma_f32_16x16x32_bf16 v[42:45], v[98:101], v[114:117], 0
	v_mfma_f32_16x16x32_bf16 v[46:49], v[102:105], v[114:117], 0
	v_mfma_f32_16x16x32_bf16 v[50:53], v[90:93], v[118:121], 0
	v_mfma_f32_16x16x32_bf16 v[54:57], v[94:97], v[118:121], 0
	v_mfma_f32_16x16x32_bf16 v[58:61], v[98:101], v[118:121], 0
	v_mfma_f32_16x16x32_bf16 v[62:65], v[102:105], v[118:121], 0
	s_waitcnt vmcnt(0) lgkmcnt(0)
	s_barrier
	v_mfma_f32_16x16x32_bf16 v[2:5], v[144:147], v[160:163], v[2:5]
	ds_read_b128 v[90:93], v142 offset:32768
	s_add_u32 m0, s22, 0x0
	v_mov_b32_e32 v177, v138
	global_load_lds_dwordx4 v177, s[18:19]
	v_mfma_f32_16x16x32_bf16 v[6:9], v[148:151], v[160:163], v[6:9]
	ds_read_b128 v[94:97], v142 offset:34816
	s_add_u32 m0, s22, 0x400
	v_add_u32_e32 v178, 0x40, v138
	global_load_lds_dwordx4 v178, s[18:19]
	v_mfma_f32_16x16x32_bf16 v[10:13], v[152:155], v[160:163], v[10:13]
	ds_read_b128 v[98:101], v142 offset:36864
	s_add_u32 m0, s22, 0x800
	v_add_u32_e32 v177, 0x8000, v138
	global_load_lds_dwordx4 v177, s[18:19]
	v_mfma_f32_16x16x32_bf16 v[14:17], v[156:159], v[160:163], v[14:17]
	ds_read_b128 v[102:105], v142 offset:38912
	s_add_u32 m0, s22, 0xc00
	v_add_u32_e32 v178, 0x8040, v138
	global_load_lds_dwordx4 v178, s[18:19]
	v_mfma_f32_16x16x32_bf16 v[18:21], v[144:147], v[164:167], v[18:21]
	ds_read_b128 v[106:109], v141 offset:32768
	s_add_u32 m0, s22, 0x4000
	v_mov_b32_e32 v177, v139
	global_load_lds_dwordx4 v177, s[20:21]
	v_mfma_f32_16x16x32_bf16 v[22:25], v[148:151], v[164:167], v[22:25]
	ds_read_b128 v[110:113], v141 offset:34816
	s_add_u32 m0, s22, 0x4400
	v_add_u32_e32 v178, 0x40, v139
	global_load_lds_dwordx4 v178, s[20:21]
	v_mfma_f32_16x16x32_bf16 v[26:29], v[152:155], v[164:167], v[26:29]
	ds_read_b128 v[114:117], v141 offset:36864
	s_add_u32 m0, s22, 0x4800
	v_add_u32_e32 v177, 0x8000, v139
	global_load_lds_dwordx4 v177, s[20:21]
	v_mfma_f32_16x16x32_bf16 v[30:33], v[156:159], v[164:167], v[30:33]
	ds_read_b128 v[118:121], v141 offset:38912
	s_add_u32 m0, s22, 0x4c00
	v_add_u32_e32 v178, 0x8040, v139
	global_load_lds_dwordx4 v178, s[20:21]
	v_mfma_f32_16x16x32_bf16 v[34:37], v[144:147], v[168:171], v[34:37]
	v_mfma_f32_16x16x32_bf16 v[38:41], v[148:151], v[168:171], v[38:41]
	v_mfma_f32_16x16x32_bf16 v[42:45], v[152:155], v[168:171], v[42:45]
	v_mfma_f32_16x16x32_bf16 v[46:49], v[156:159], v[168:171], v[46:49]
	v_mfma_f32_16x16x32_bf16 v[50:53], v[144:147], v[172:175], v[50:53]
	v_mfma_f32_16x16x32_bf16 v[54:57], v[148:151], v[172:175], v[54:57]
	v_mfma_f32_16x16x32_bf16 v[58:61], v[152:155], v[172:175], v[58:61]
	v_mfma_f32_16x16x32_bf16 v[62:65], v[156:159], v[172:175], v[62:65]
	v_add_u32_e32 v138, 0x80, v138
	v_add_u32_e32 v139, 0x80, v139
	s_waitcnt lgkmcnt(0)
	v_mfma_f32_16x16x32_bf16 v[2:5], v[90:93], v[106:109], v[2:5]
	ds_read_b128 v[144:147], v142 offset:33792
	v_mfma_f32_16x16x32_bf16 v[6:9], v[94:97], v[106:109], v[6:9]
	ds_read_b128 v[148:151], v142 offset:35840
	v_mfma_f32_16x16x32_bf16 v[10:13], v[98:101], v[106:109], v[10:13]
	ds_read_b128 v[152:155], v142 offset:37888
	v_mfma_f32_16x16x32_bf16 v[14:17], v[102:105], v[106:109], v[14:17]
	ds_read_b128 v[156:159], v142 offset:39936
	v_mfma_f32_16x16x32_bf16 v[18:21], v[90:93], v[110:113], v[18:21]
	ds_read_b128 v[160:163], v141 offset:33792
	v_mfma_f32_16x16x32_bf16 v[22:25], v[94:97], v[110:113], v[22:25]
	ds_read_b128 v[164:167], v141 offset:35840
	v_mfma_f32_16x16x32_bf16 v[26:29], v[98:101], v[110:113], v[26:29]
	ds_read_b128 v[168:171], v141 offset:37888
	v_mfma_f32_16x16x32_bf16 v[30:33], v[102:105], v[110:113], v[30:33]
	ds_read_b128 v[172:175], v141 offset:39936
	v_mfma_f32_16x16x32_bf16 v[34:37], v[90:93], v[114:117], v[34:37]
	v_mfma_f32_16x16x32_bf16 v[38:41], v[94:97], v[114:117], v[38:41]
	v_mfma_f32_16x16x32_bf16 v[42:45], v[98:101], v[114:117], v[42:45]
	v_mfma_f32_16x16x32_bf16 v[46:49], v[102:105], v[114:117], v[46:49]
	v_mfma_f32_16x16x32_bf16 v[50:53], v[90:93], v[118:121], v[50:53]
	v_mfma_f32_16x16x32_bf16 v[54:57], v[94:97], v[118:121], v[54:57]
	v_mfma_f32_16x16x32_bf16 v[58:61], v[98:101], v[118:121], v[58:61]
	v_mfma_f32_16x16x32_bf16 v[62:65], v[102:105], v[118:121], v[62:65]
	s_waitcnt vmcnt(0) lgkmcnt(0)
	s_barrier
	v_mfma_f32_16x16x32_bf16 v[2:5], v[144:147], v[160:163], v[2:5]
	ds_read_b128 v[90:93], v142
	s_add_u32 m0, s22, 0x8000
	v_mov_b32_e32 v177, v138
	global_load_lds_dwordx4 v177, s[18:19]
	v_mfma_f32_16x16x32_bf16 v[6:9], v[148:151], v[160:163], v[6:9]
	ds_read_b128 v[94:97], v142 offset:2048
	s_add_u32 m0, s22, 0x8400
	v_add_u32_e32 v178, 0x40, v138
	global_load_lds_dwordx4 v178, s[18:19]
	v_mfma_f32_16x16x32_bf16 v[10:13], v[152:155], v[160:163], v[10:13]
	ds_read_b128 v[98:101], v142 offset:4096
	s_add_u32 m0, s22, 0x8800
	v_add_u32_e32 v177, 0x8000, v138
	global_load_lds_dwordx4 v177, s[18:19]
	v_mfma_f32_16x16x32_bf16 v[14:17], v[156:159], v[160:163], v[14:17]
	ds_read_b128 v[102:105], v142 offset:6144
	s_add_u32 m0, s22, 0x8c00
	v_add_u32_e32 v178, 0x8040, v138
	global_load_lds_dwordx4 v178, s[18:19]
	v_mfma_f32_16x16x32_bf16 v[18:21], v[144:147], v[164:167], v[18:21]
	ds_read_b128 v[106:109], v141
	s_add_u32 m0, s22, 0xc000
	v_mov_b32_e32 v177, v139
	global_load_lds_dwordx4 v177, s[20:21]
	v_mfma_f32_16x16x32_bf16 v[22:25], v[148:151], v[164:167], v[22:25]
	ds_read_b128 v[110:113], v141 offset:2048
	s_add_u32 m0, s22, 0xc400
	v_add_u32_e32 v178, 0x40, v139
	global_load_lds_dwordx4 v178, s[20:21]
	v_mfma_f32_16x16x32_bf16 v[26:29], v[152:155], v[164:167], v[26:29]
	ds_read_b128 v[114:117], v141 offset:4096
	s_add_u32 m0, s22, 0xc800
	v_add_u32_e32 v177, 0x8000, v139
	global_load_lds_dwordx4 v177, s[20:21]
	v_mfma_f32_16x16x32_bf16 v[30:33], v[156:159], v[164:167], v[30:33]
	ds_read_b128 v[118:121], v141 offset:6144
	s_add_u32 m0, s22, 0xcc00
	v_add_u32_e32 v178, 0x8040, v139
	global_load_lds_dwordx4 v178, s[20:21]
	v_mfma_f32_16x16x32_bf16 v[34:37], v[144:147], v[168:171], v[34:37]
	v_mfma_f32_16x16x32_bf16 v[38:41], v[148:151], v[168:171], v[38:41]
	v_mfma_f32_16x16x32_bf16 v[42:45], v[152:155], v[168:171], v[42:45]
	v_mfma_f32_16x16x32_bf16 v[46:49], v[156:159], v[168:171], v[46:49]
	v_mfma_f32_16x16x32_bf16 v[50:53], v[144:147], v[172:175], v[50:53]
	v_mfma_f32_16x16x32_bf16 v[54:57], v[148:151], v[172:175], v[54:57]
	v_mfma_f32_16x16x32_bf16 v[58:61], v[152:155], v[172:175], v[58:61]
	v_mfma_f32_16x16x32_bf16 v[62:65], v[156:159], v[172:175], v[62:65]
	v_add_u32_e32 v138, 0x80, v138
	v_add_u32_e32 v139, 0x80, v139
	s_mov_b32 s16, 6
.Lgm_loop:
	s_waitcnt lgkmcnt(0)
	v_mfma_f32_16x16x32_bf16 v[2:5], v[90:93], v[106:109], v[2:5]
	ds_read_b128 v[144:147], v142 offset:1024
	v_mfma_f32_16x16x32_bf16 v[6:9], v[94:97], v[106:109], v[6:9]
	ds_read_b128 v[148:151], v142 offset:3072
	v_mfma_f32_16x16x32_bf16 v[10:13], v[98:101], v[106:109], v[10:13]
	ds_read_b128 v[152:155], v142 offset:5120
	v_mfma_f32_16x16x32_bf16 v[14:17], v[102:105], v[106:109], v[14:17]
	ds_read_b128 v[156:159], v142 offset:7168
	v_mfma_f32_16x16x32_bf16 v[18:21], v[90:93], v[110:113], v[18:21]
	ds_read_b128 v[160:163], v141 offset:1024
	v_mfma_f32_16x16x32_bf16 v[22:25], v[94:97], v[110:113], v[22:25]
	ds_read_b128 v[164:167], v141 offset:3072
	v_mfma_f32_16x16x32_bf16 v[26:29], v[98:101], v[110:113], v[26:29]
	ds_read_b128 v[168:171], v141 offset:5120
	v_mfma_f32_16x16x32_bf16 v[30:33], v[102:105], v[110:113], v[30:33]
	ds_read_b128 v[172:175], v141 offset:7168
	v_mfma_f32_16x16x32_bf16 v[34:37], v[90:93], v[114:117], v[34:37]
	v_mfma_f32_16x16x32_bf16 v[38:41], v[94:97], v[114:117], v[38:41]
	v_mfma_f32_16x16x32_bf16 v[42:45], v[98:101], v[114:117], v[42:45]
	v_mfma_f32_16x16x32_bf16 v[46:49], v[102:105], v[114:117], v[46:49]
	v_mfma_f32_16x16x32_bf16 v[50:53], v[90:93], v[118:121], v[50:53]
	v_mfma_f32_16x16x32_bf16 v[54:57], v[94:97], v[118:121], v[54:57]
	v_mfma_f32_16x16x32_bf16 v[58:61], v[98:101], v[118:121], v[58:61]
	v_mfma_f32_16x16x32_bf16 v[62:65], v[102:105], v[118:121], v[62:65]
	s_waitcnt vmcnt(0) lgkmcnt(0)
	s_barrier
	v_mfma_f32_16x16x32_bf16 v[2:5], v[144:147], v[160:163], v[2:5]
	ds_read_b128 v[90:93], v142 offset:32768
	s_add_u32 m0, s22, 0x0
	v_mov_b32_e32 v177, v138
	global_load_lds_dwordx4 v177, s[18:19]
	v_mfma_f32_16x16x32_bf16 v[6:9], v[148:151], v[160:163], v[6:9]
	ds_read_b128 v[94:97], v142 offset:34816
	s_add_u32 m0, s22, 0x400
	v_add_u32_e32 v178, 0x40, v138
	global_load_lds_dwordx4 v178, s[18:19]
	v_mfma_f32_16x16x32_bf16 v[10:13], v[152:155], v[160:163], v[10:13]
	ds_read_b128 v[98:101], v142 offset:36864
	s_add_u32 m0, s22, 0x800
	v_add_u32_e32 v177, 0x8000, v138
	global_load_lds_dwordx4 v177, s[18:19]
	v_mfma_f32_16x16x32_bf16 v[14:17], v[156:159], v[160:163], v[14:17]
	ds_read_b128 v[102:105], v142 offset:38912
	s_add_u32 m0, s22, 0xc00
	v_add_u32_e32 v178, 0x8040, v138
	global_load_lds_dwordx4 v178, s[18:19]
	v_mfma_f32_16x16x32_bf16 v[18:21], v[144:147], v[164:167], v[18:21]
	ds_read_b128 v[106:109], v141 offset:32768
	s_add_u32 m0, s22, 0x4000
	v_mov_b32_e32 v177, v139
	global_load_lds_dwordx4 v177, s[20:21]
	v_mfma_f32_16x16x32_bf16 v[22:25], v[148:151], v[164:167], v[22:25]
	ds_read_b128 v[110:113], v141 offset:34816
	s_add_u32 m0, s22, 0x4400
	v_add_u32_e32 v178, 0x40, v139
	global_load_lds_dwordx4 v178, s[20:21]
	v_mfma_f32_16x16x32_bf16 v[26:29], v[152:155], v[164:167], v[26:29]
	ds_read_b128 v[114:117], v141 offset:36864
	s_add_u32 m0, s22, 0x4800
	v_add_u32_e32 v177, 0x8000, v139
	global_load_lds_dwordx4 v177, s[20:21]
	v_mfma_f32_16x16x32_bf16 v[30:33], v[156:159], v[164:167], v[30:33]
	ds_read_b128 v[118:121], v141 offset:38912
	s_add_u32 m0, s22, 0x4c00
	v_add_u32_e32 v178, 0x8040, v139
	global_load_lds_dwordx4 v178, s[20:21]
	v_mfma_f32_16x16x32_bf16 v[34:37], v[144:147], v[168:171], v[34:37]
	v_mfma_f32_16x16x32_bf16 v[38:41], v[148:151], v[168:171], v[38:41]
	v_mfma_f32_16x16x32_bf16 v[42:45], v[152:155], v[168:171], v[42:45]
	v_mfma_f32_16x16x32_bf16 v[46:49], v[156:159], v[168:171], v[46:49]
	v_mfma_f32_16x16x32_bf16 v[50:53], v[144:147], v[172:175], v[50:53]
	v_mfma_f32_16x16x32_bf16 v[54:57], v[148:151], v[172:175], v[54:57]
	v_mfma_f32_16x16x32_bf16 v[58:61], v[152:155], v[172:175], v[58:61]
	v_mfma_f32_16x16x32_bf16 v[62:65], v[156:159], v[172:175], v[62:65]
	v_add_u32_e32 v138, 0x80, v138
	v_add_u32_e32 v139, 0x80, v139
	s_waitcnt lgkmcnt(0)
	v_mfma_f32_16x16x32_bf16 v[2:5], v[90:93], v[106:109], v[2:5]
	ds_read_b128 v[144:147], v142 offset:33792
	v_mfma_f32_16x16x32_bf16 v[6:9], v[94:97], v[106:109], v[6:9]
	ds_read_b128 v[148:151], v142 offset:35840
	v_mfma_f32_16x16x32_bf16 v[10:13], v[98:101], v[106:109], v[10:13]
	ds_read_b128 v[152:155], v142 offset:37888
	v_mfma_f32_16x16x32_bf16 v[14:17], v[102:105], v[106:109], v[14:17]
	ds_read_b128 v[156:159], v142 offset:39936
	v_mfma_f32_16x16x32_bf16 v[18:21], v[90:93], v[110:113], v[18:21]
	ds_read_b128 v[160:163], v141 offset:33792
	v_mfma_f32_16x16x32_bf16 v[22:25], v[94:97], v[110:113], v[22:25]
	ds_read_b128 v[164:167], v141 offset:35840
	v_mfma_f32_16x16x32_bf16 v[26:29], v[98:101], v[110:113], v[26:29]
	ds_read_b128 v[168:171], v141 offset:37888
	v_mfma_f32_16x16x32_bf16 v[30:33], v[102:105], v[110:113], v[30:33]
	ds_read_b128 v[172:175], v141 offset:39936
	v_mfma_f32_16x16x32_bf16 v[34:37], v[90:93], v[114:117], v[34:37]
	v_mfma_f32_16x16x32_bf16 v[38:41], v[94:97], v[114:117], v[38:41]
	v_mfma_f32_16x16x32_bf16 v[42:45], v[98:101], v[114:117], v[42:45]
	v_mfma_f32_16x16x32_bf16 v[46:49], v[102:105], v[114:117], v[46:49]
	v_mfma_f32_16x16x32_bf16 v[50:53], v[90:93], v[118:121], v[50:53]
	v_mfma_f32_16x16x32_bf16 v[54:57], v[94:97], v[118:121], v[54:57]
	v_mfma_f32_16x16x32_bf16 v[58:61], v[98:101], v[118:121], v[58:61]
	v_mfma_f32_16x16x32_bf16 v[62:65], v[102:105], v[118:121], v[62:65]
	s_waitcnt vmcnt(0) lgkmcnt(0)
	s_barrier
	v_mfma_f32_16x16x32_bf16 v[2:5], v[144:147], v[160:163], v[2:5]
	ds_read_b128 v[90:93], v142
	s_add_u32 m0, s22, 0x8000
	v_mov_b32_e32 v177, v138
	global_load_lds_dwordx4 v177, s[18:19]
	v_mfma_f32_16x16x32_bf16 v[6:9], v[148:151], v[160:163], v[6:9]
	ds_read_b128 v[94:97], v142 offset:2048
	s_add_u32 m0, s22, 0x8400
	v_add_u32_e32 v178, 0x40, v138
	global_load_lds_dwordx4 v178, s[18:19]
	v_mfma_f32_16x16x32_bf16 v[10:13], v[152:155], v[160:163], v[10:13]
	ds_read_b128 v[98:101], v142 offset:4096
	s_add_u32 m0, s22, 0x8800
	v_add_u32_e32 v177, 0x8000, v138
	global_load_lds_dwordx4 v177, s[18:19]
	v_mfma_f32_16x16x32_bf16 v[14:17], v[156:159], v[160:163], v[14:17]
	ds_read_b128 v[102:105], v142 offset:6144
	s_add_u32 m0, s22, 0x8c00
	v_add_u32_e32 v178, 0x8040, v138
	global_load_lds_dwordx4 v178, s[18:19]
	v_mfma_f32_16x16x32_bf16 v[18:21], v[144:147], v[164:167], v[18:21]
	ds_read_b128 v[106:109], v141
	s_add_u32 m0, s22, 0xc000
	v_mov_b32_e32 v177, v139
	global_load_lds_dwordx4 v177, s[20:21]
	v_mfma_f32_16x16x32_bf16 v[22:25], v[148:151], v[164:167], v[22:25]
	ds_read_b128 v[110:113], v141 offset:2048
	s_add_u32 m0, s22, 0xc400
	v_add_u32_e32 v178, 0x40, v139
	global_load_lds_dwordx4 v178, s[20:21]
	v_mfma_f32_16x16x32_bf16 v[26:29], v[152:155], v[164:167], v[26:29]
	ds_read_b128 v[114:117], v141 offset:4096
	s_add_u32 m0, s22, 0xc800
	v_add_u32_e32 v177, 0x8000, v139
	global_load_lds_dwordx4 v177, s[20:21]
	v_mfma_f32_16x16x32_bf16 v[30:33], v[156:159], v[164:167], v[30:33]
	ds_read_b128 v[118:121], v141 offset:6144
	s_add_u32 m0, s22, 0xcc00
	v_add_u32_e32 v178, 0x8040, v139
	global_load_lds_dwordx4 v178, s[20:21]
	v_mfma_f32_16x16x32_bf16 v[34:37], v[144:147], v[168:171], v[34:37]
	v_mfma_f32_16x16x32_bf16 v[38:41], v[148:151], v[168:171], v[38:41]
	v_mfma_f32_16x16x32_bf16 v[42:45], v[152:155], v[168:171], v[42:45]
	v_mfma_f32_16x16x32_bf16 v[46:49], v[156:159], v[168:171], v[46:49]
	v_mfma_f32_16x16x32_bf16 v[50:53], v[144:147], v[172:175], v[50:53]
	v_mfma_f32_16x16x32_bf16 v[54:57], v[148:151], v[172:175], v[54:57]
	v_mfma_f32_16x16x32_bf16 v[58:61], v[152:155], v[172:175], v[58:61]
	v_mfma_f32_16x16x32_bf16 v[62:65], v[156:159], v[172:175], v[62:65]
	v_add_u32_e32 v138, 0x80, v138
	v_add_u32_e32 v139, 0x80, v139
	s_sub_u32 s16, s16, 1
	s_cmp_lg_u32 s16, 0
	s_cbranch_scc1 .Lgm_loop
	s_lshl_b32 s3, s26, 12
	v_add_u32_e32 v195, s3, v176
	global_load_dwordx4 v[240:243], v195, s[24:25]
	global_load_dwordx4 v[244:247], v195, s[24:25] offset:64
	global_load_dwordx4 v[248:251], v195, s[24:25] offset:128
	global_load_dwordx4 v[252:255], v195, s[24:25] offset:192
	s_cmp_eq_u32 s26, 3
	s_cbranch_scc1 .Lgm_lastbr
	v_add_u32_e32 v137, 0x7fe00, v137
	s_mov_b32 s27, 1
	s_branch .Lgm_tail
.Lgm_lastbr:
	s_add_u32 s12, s12, s83
	s_cmp_ge_u32 s12, 128
	s_cbranch_scc1 .Lgm_nonext
	s_lshr_b32 s3, s12, 6
	s_lshl_b32 s3, s3, 3
	s_add_u32 s3, s3, s65
	s_lshl_b32 s3, s3, 3
	s_bfe_u32 s17, s12, 0x30003
	s_add_u32 s13, s3, s17
	s_and_b32 s14, s12, 7
	s_lshl_b32 s13, s13, 7
	s_lshl_b32 s14, s14, 7
	s_lshl_b32 s3, s15, 5
	s_add_u32 s17, s3, s13
	s_lshl_b32 s17, s17, 11
	s_add_u32 s17, s17, 0x9c27800
	s_add_u32 s6, s4, s17
	s_addc_u32 s7, s5, 0
	s_add_u32 s17, s3, s14
	s_lshl_b32 s17, s17, 9
	s_add_u32 s17, s17, 0x1727800
	s_add_u32 s8, s4, s17
	s_addc_u32 s9, s5, 0
	v_mov_b32_e32 v136, v134
	v_mov_b32_e32 v137, v135
	s_mov_b32 s27, 1
.Lgm_tail:
	s_waitcnt lgkmcnt(0)
	v_mfma_f32_16x16x32_bf16 v[2:5], v[90:93], v[106:109], v[2:5]
	ds_read_b128 v[144:147], v142 offset:1024
	v_mfma_f32_16x16x32_bf16 v[6:9], v[94:97], v[106:109], v[6:9]
	ds_read_b128 v[148:151], v142 offset:3072
	v_mfma_f32_16x16x32_bf16 v[10:13], v[98:101], v[106:109], v[10:13]
	ds_read_b128 v[152:155], v142 offset:5120
	v_mfma_f32_16x16x32_bf16 v[14:17], v[102:105], v[106:109], v[14:17]
	ds_read_b128 v[156:159], v142 offset:7168
	v_mfma_f32_16x16x32_bf16 v[18:21], v[90:93], v[110:113], v[18:21]
	ds_read_b128 v[160:163], v141 offset:1024
	v_mfma_f32_16x16x32_bf16 v[22:25], v[94:97], v[110:113], v[22:25]
	ds_read_b128 v[164:167], v141 offset:3072
	v_mfma_f32_16x16x32_bf16 v[26:29], v[98:101], v[110:113], v[26:29]
	ds_read_b128 v[168:171], v141 offset:5120
	v_mfma_f32_16x16x32_bf16 v[30:33], v[102:105], v[110:113], v[30:33]
	ds_read_b128 v[172:175], v141 offset:7168
	v_mfma_f32_16x16x32_bf16 v[34:37], v[90:93], v[114:117], v[34:37]
	v_mfma_f32_16x16x32_bf16 v[38:41], v[94:97], v[114:117], v[38:41]
	v_mfma_f32_16x16x32_bf16 v[42:45], v[98:101], v[114:117], v[42:45]
	v_mfma_f32_16x16x32_bf16 v[46:49], v[102:105], v[114:117], v[46:49]
	v_mfma_f32_16x16x32_bf16 v[50:53], v[90:93], v[118:121], v[50:53]
	v_mfma_f32_16x16x32_bf16 v[54:57], v[94:97], v[118:121], v[54:57]
	v_mfma_f32_16x16x32_bf16 v[58:61], v[98:101], v[118:121], v[58:61]
	v_mfma_f32_16x16x32_bf16 v[62:65], v[102:105], v[118:121], v[62:65]
	s_waitcnt vmcnt(0) lgkmcnt(0)
	s_barrier
	v_mfma_f32_16x16x32_bf16 v[2:5], v[144:147], v[160:163], v[2:5]
	ds_read_b128 v[90:93], v142 offset:32768
	s_add_u32 m0, s22, 0x0
	v_mov_b32_e32 v177, v136
	global_load_lds_dwordx4 v177, s[6:7]
	v_mfma_f32_16x16x32_bf16 v[6:9], v[148:151], v[160:163], v[6:9]
	ds_read_b128 v[94:97], v142 offset:34816
	s_add_u32 m0, s22, 0x400
	v_add_u32_e32 v178, 0x40, v136
	global_load_lds_dwordx4 v178, s[6:7]
	v_mfma_f32_16x16x32_bf16 v[10:13], v[152:155], v[160:163], v[10:13]
	ds_read_b128 v[98:101], v142 offset:36864
	s_add_u32 m0, s22, 0x800
	v_add_u32_e32 v177, 0x8000, v136
	global_load_lds_dwordx4 v177, s[6:7]
	v_mfma_f32_16x16x32_bf16 v[14:17], v[156:159], v[160:163], v[14:17]
	ds_read_b128 v[102:105], v142 offset:38912
	s_add_u32 m0, s22, 0xc00
	v_add_u32_e32 v178, 0x8040, v136
	global_load_lds_dwordx4 v178, s[6:7]
	v_mfma_f32_16x16x32_bf16 v[18:21], v[144:147], v[164:167], v[18:21]
	ds_read_b128 v[106:109], v141 offset:32768
	s_add_u32 m0, s22, 0x4000
	v_mov_b32_e32 v177, v137
	global_load_lds_dwordx4 v177, s[8:9]
	v_mfma_f32_16x16x32_bf16 v[22:25], v[148:151], v[164:167], v[22:25]
	ds_read_b128 v[110:113], v141 offset:34816
	s_add_u32 m0, s22, 0x4400
	v_add_u32_e32 v178, 0x40, v137
	global_load_lds_dwordx4 v178, s[8:9]
	v_mfma_f32_16x16x32_bf16 v[26:29], v[152:155], v[164:167], v[26:29]
	ds_read_b128 v[114:117], v141 offset:36864
	s_add_u32 m0, s22, 0x4800
	v_add_u32_e32 v177, 0x2000, v137
	global_load_lds_dwordx4 v177, s[8:9]
	v_mfma_f32_16x16x32_bf16 v[30:33], v[156:159], v[164:167], v[30:33]
	ds_read_b128 v[118:121], v141 offset:38912
	s_add_u32 m0, s22, 0x4c00
	v_add_u32_e32 v178, 0x2040, v137
	global_load_lds_dwordx4 v178, s[8:9]
	v_mfma_f32_16x16x32_bf16 v[34:37], v[144:147], v[168:171], v[34:37]
	v_mfma_f32_16x16x32_bf16 v[38:41], v[148:151], v[168:171], v[38:41]
	v_mfma_f32_16x16x32_bf16 v[42:45], v[152:155], v[168:171], v[42:45]
	v_mfma_f32_16x16x32_bf16 v[46:49], v[156:159], v[168:171], v[46:49]
	v_mfma_f32_16x16x32_bf16 v[50:53], v[144:147], v[172:175], v[50:53]
	v_mfma_f32_16x16x32_bf16 v[54:57], v[148:151], v[172:175], v[54:57]
	v_mfma_f32_16x16x32_bf16 v[58:61], v[152:155], v[172:175], v[58:61]
	v_mfma_f32_16x16x32_bf16 v[62:65], v[156:159], v[172:175], v[62:65]
	v_add_u32_e32 v136, 0x80, v136
	v_add_u32_e32 v137, 0x80, v137
	s_waitcnt lgkmcnt(0)
	v_mfma_f32_16x16x32_bf16 v[2:5], v[90:93], v[106:109], v[2:5]
	ds_read_b128 v[144:147], v142 offset:33792
	v_mfma_f32_16x16x32_bf16 v[6:9], v[94:97], v[106:109], v[6:9]
	ds_read_b128 v[148:151], v142 offset:35840
	v_mfma_f32_16x16x32_bf16 v[10:13], v[98:101], v[106:109], v[10:13]
	ds_read_b128 v[152:155], v142 offset:37888
	v_mfma_f32_16x16x32_bf16 v[14:17], v[102:105], v[106:109], v[14:17]
	ds_read_b128 v[156:159], v142 offset:39936
	v_mfma_f32_16x16x32_bf16 v[18:21], v[90:93], v[110:113], v[18:21]
	ds_read_b128 v[160:163], v141 offset:33792
	v_mfma_f32_16x16x32_bf16 v[22:25], v[94:97], v[110:113], v[22:25]
	ds_read_b128 v[164:167], v141 offset:35840
	v_mfma_f32_16x16x32_bf16 v[26:29], v[98:101], v[110:113], v[26:29]
	ds_read_b128 v[168:171], v141 offset:37888
	v_mfma_f32_16x16x32_bf16 v[30:33], v[102:105], v[110:113], v[30:33]
	ds_read_b128 v[172:175], v141 offset:39936
	v_mfma_f32_16x16x32_bf16 v[34:37], v[90:93], v[114:117], v[34:37]
	v_mfma_f32_16x16x32_bf16 v[38:41], v[94:97], v[114:117], v[38:41]
	v_mfma_f32_16x16x32_bf16 v[42:45], v[98:101], v[114:117], v[42:45]
	v_mfma_f32_16x16x32_bf16 v[46:49], v[102:105], v[114:117], v[46:49]
	v_mfma_f32_16x16x32_bf16 v[50:53], v[90:93], v[118:121], v[50:53]
	v_mfma_f32_16x16x32_bf16 v[54:57], v[94:97], v[118:121], v[54:57]
	v_mfma_f32_16x16x32_bf16 v[58:61], v[98:101], v[118:121], v[58:61]
	v_mfma_f32_16x16x32_bf16 v[62:65], v[102:105], v[118:121], v[62:65]
	s_waitcnt vmcnt(0) lgkmcnt(0)
	s_barrier
	v_mfma_f32_16x16x32_bf16 v[2:5], v[144:147], v[160:163], v[2:5]
	ds_read_b128 v[90:93], v142
	s_add_u32 m0, s22, 0x8000
	v_mov_b32_e32 v177, v136
	global_load_lds_dwordx4 v177, s[6:7]
	v_mfma_f32_16x16x32_bf16 v[6:9], v[148:151], v[160:163], v[6:9]
	ds_read_b128 v[94:97], v142 offset:2048
	s_add_u32 m0, s22, 0x8400
	v_add_u32_e32 v178, 0x40, v136
	global_load_lds_dwordx4 v178, s[6:7]
	v_mfma_f32_16x16x32_bf16 v[10:13], v[152:155], v[160:163], v[10:13]
	ds_read_b128 v[98:101], v142 offset:4096
	s_add_u32 m0, s22, 0x8800
	v_add_u32_e32 v177, 0x8000, v136
	global_load_lds_dwordx4 v177, s[6:7]
	v_mfma_f32_16x16x32_bf16 v[14:17], v[156:159], v[160:163], v[14:17]
	ds_read_b128 v[102:105], v142 offset:6144
	s_add_u32 m0, s22, 0x8c00
	v_add_u32_e32 v178, 0x8040, v136
	global_load_lds_dwordx4 v178, s[6:7]
	v_mfma_f32_16x16x32_bf16 v[18:21], v[144:147], v[164:167], v[18:21]
	ds_read_b128 v[106:109], v141
	s_add_u32 m0, s22, 0xc000
	v_mov_b32_e32 v177, v137
	global_load_lds_dwordx4 v177, s[8:9]
	v_mfma_f32_16x16x32_bf16 v[22:25], v[148:151], v[164:167], v[22:25]
	ds_read_b128 v[110:113], v141 offset:2048
	s_add_u32 m0, s22, 0xc400
	v_add_u32_e32 v178, 0x40, v137
	global_load_lds_dwordx4 v178, s[8:9]
	v_mfma_f32_16x16x32_bf16 v[26:29], v[152:155], v[164:167], v[26:29]
	ds_read_b128 v[114:117], v141 offset:4096
	s_add_u32 m0, s22, 0xc800
	v_add_u32_e32 v177, 0x2000, v137
	global_load_lds_dwordx4 v177, s[8:9]
	v_mfma_f32_16x16x32_bf16 v[30:33], v[156:159], v[164:167], v[30:33]
	ds_read_b128 v[118:121], v141 offset:6144
	s_add_u32 m0, s22, 0xcc00
	v_add_u32_e32 v178, 0x2040, v137
	global_load_lds_dwordx4 v178, s[8:9]
	v_mfma_f32_16x16x32_bf16 v[34:37], v[144:147], v[168:171], v[34:37]
	v_mfma_f32_16x16x32_bf16 v[38:41], v[148:151], v[168:171], v[38:41]
	v_mfma_f32_16x16x32_bf16 v[42:45], v[152:155], v[168:171], v[42:45]
	v_mfma_f32_16x16x32_bf16 v[46:49], v[156:159], v[168:171], v[46:49]
	v_mfma_f32_16x16x32_bf16 v[50:53], v[144:147], v[172:175], v[50:53]
	v_mfma_f32_16x16x32_bf16 v[54:57], v[148:151], v[172:175], v[54:57]
	v_mfma_f32_16x16x32_bf16 v[58:61], v[152:155], v[172:175], v[58:61]
	v_mfma_f32_16x16x32_bf16 v[62:65], v[156:159], v[172:175], v[62:65]
	v_add_u32_e32 v136, 0x80, v136
	v_add_u32_e32 v137, 0x80, v137
	s_branch .Lgm_mrg
.Lgm_nonext:
	s_mov_b32 s27, 0
	s_waitcnt lgkmcnt(0)
	v_mfma_f32_16x16x32_bf16 v[2:5], v[90:93], v[106:109], v[2:5]
	ds_read_b128 v[144:147], v142 offset:1024
	v_mfma_f32_16x16x32_bf16 v[6:9], v[94:97], v[106:109], v[6:9]
	ds_read_b128 v[148:151], v142 offset:3072
	v_mfma_f32_16x16x32_bf16 v[10:13], v[98:101], v[106:109], v[10:13]
	ds_read_b128 v[152:155], v142 offset:5120
	v_mfma_f32_16x16x32_bf16 v[14:17], v[102:105], v[106:109], v[14:17]
	ds_read_b128 v[156:159], v142 offset:7168
	v_mfma_f32_16x16x32_bf16 v[18:21], v[90:93], v[110:113], v[18:21]
	ds_read_b128 v[160:163], v141 offset:1024
	v_mfma_f32_16x16x32_bf16 v[22:25], v[94:97], v[110:113], v[22:25]
	ds_read_b128 v[164:167], v141 offset:3072
	v_mfma_f32_16x16x32_bf16 v[26:29], v[98:101], v[110:113], v[26:29]
	ds_read_b128 v[168:171], v141 offset:5120
	v_mfma_f32_16x16x32_bf16 v[30:33], v[102:105], v[110:113], v[30:33]
	ds_read_b128 v[172:175], v141 offset:7168
	v_mfma_f32_16x16x32_bf16 v[34:37], v[90:93], v[114:117], v[34:37]
	v_mfma_f32_16x16x32_bf16 v[38:41], v[94:97], v[114:117], v[38:41]
	v_mfma_f32_16x16x32_bf16 v[42:45], v[98:101], v[114:117], v[42:45]
	v_mfma_f32_16x16x32_bf16 v[46:49], v[102:105], v[114:117], v[46:49]
	v_mfma_f32_16x16x32_bf16 v[50:53], v[90:93], v[118:121], v[50:53]
	v_mfma_f32_16x16x32_bf16 v[54:57], v[94:97], v[118:121], v[54:57]
	v_mfma_f32_16x16x32_bf16 v[58:61], v[98:101], v[118:121], v[58:61]
	v_mfma_f32_16x16x32_bf16 v[62:65], v[102:105], v[118:121], v[62:65]
	s_waitcnt vmcnt(0) lgkmcnt(0)
	s_barrier
	v_mfma_f32_16x16x32_bf16 v[2:5], v[144:147], v[160:163], v[2:5]
	ds_read_b128 v[90:93], v142 offset:32768
	v_mfma_f32_16x16x32_bf16 v[6:9], v[148:151], v[160:163], v[6:9]
	ds_read_b128 v[94:97], v142 offset:34816
	v_mfma_f32_16x16x32_bf16 v[10:13], v[152:155], v[160:163], v[10:13]
	ds_read_b128 v[98:101], v142 offset:36864
	v_mfma_f32_16x16x32_bf16 v[14:17], v[156:159], v[160:163], v[14:17]
	ds_read_b128 v[102:105], v142 offset:38912
	v_mfma_f32_16x16x32_bf16 v[18:21], v[144:147], v[164:167], v[18:21]
	ds_read_b128 v[106:109], v141 offset:32768
	v_mfma_f32_16x16x32_bf16 v[22:25], v[148:151], v[164:167], v[22:25]
	ds_read_b128 v[110:113], v141 offset:34816
	v_mfma_f32_16x16x32_bf16 v[26:29], v[152:155], v[164:167], v[26:29]
	ds_read_b128 v[114:117], v141 offset:36864
	v_mfma_f32_16x16x32_bf16 v[30:33], v[156:159], v[164:167], v[30:33]
	ds_read_b128 v[118:121], v141 offset:38912
	v_mfma_f32_16x16x32_bf16 v[34:37], v[144:147], v[168:171], v[34:37]
	v_mfma_f32_16x16x32_bf16 v[38:41], v[148:151], v[168:171], v[38:41]
	v_mfma_f32_16x16x32_bf16 v[42:45], v[152:155], v[168:171], v[42:45]
	v_mfma_f32_16x16x32_bf16 v[46:49], v[156:159], v[168:171], v[46:49]
	v_mfma_f32_16x16x32_bf16 v[50:53], v[144:147], v[172:175], v[50:53]
	v_mfma_f32_16x16x32_bf16 v[54:57], v[148:151], v[172:175], v[54:57]
	v_mfma_f32_16x16x32_bf16 v[58:61], v[152:155], v[172:175], v[58:61]
	v_mfma_f32_16x16x32_bf16 v[62:65], v[156:159], v[172:175], v[62:65]
	s_waitcnt lgkmcnt(0)
	v_mfma_f32_16x16x32_bf16 v[2:5], v[90:93], v[106:109], v[2:5]
	ds_read_b128 v[144:147], v142 offset:33792
	v_mfma_f32_16x16x32_bf16 v[6:9], v[94:97], v[106:109], v[6:9]
	ds_read_b128 v[148:151], v142 offset:35840
	v_mfma_f32_16x16x32_bf16 v[10:13], v[98:101], v[106:109], v[10:13]
	ds_read_b128 v[152:155], v142 offset:37888
	v_mfma_f32_16x16x32_bf16 v[14:17], v[102:105], v[106:109], v[14:17]
	ds_read_b128 v[156:159], v142 offset:39936
	v_mfma_f32_16x16x32_bf16 v[18:21], v[90:93], v[110:113], v[18:21]
	ds_read_b128 v[160:163], v141 offset:33792
	v_mfma_f32_16x16x32_bf16 v[22:25], v[94:97], v[110:113], v[22:25]
	ds_read_b128 v[164:167], v141 offset:35840
	v_mfma_f32_16x16x32_bf16 v[26:29], v[98:101], v[110:113], v[26:29]
	ds_read_b128 v[168:171], v141 offset:37888
	v_mfma_f32_16x16x32_bf16 v[30:33], v[102:105], v[110:113], v[30:33]
	ds_read_b128 v[172:175], v141 offset:39936
	v_mfma_f32_16x16x32_bf16 v[34:37], v[90:93], v[114:117], v[34:37]
	v_mfma_f32_16x16x32_bf16 v[38:41], v[94:97], v[114:117], v[38:41]
	v_mfma_f32_16x16x32_bf16 v[42:45], v[98:101], v[114:117], v[42:45]
	v_mfma_f32_16x16x32_bf16 v[46:49], v[102:105], v[114:117], v[46:49]
	v_mfma_f32_16x16x32_bf16 v[50:53], v[90:93], v[118:121], v[50:53]
	v_mfma_f32_16x16x32_bf16 v[54:57], v[94:97], v[118:121], v[54:57]
	v_mfma_f32_16x16x32_bf16 v[58:61], v[98:101], v[118:121], v[58:61]
	v_mfma_f32_16x16x32_bf16 v[62:65], v[102:105], v[118:121], v[62:65]
	s_waitcnt vmcnt(0) lgkmcnt(0)
	s_barrier
	v_mfma_f32_16x16x32_bf16 v[2:5], v[144:147], v[160:163], v[2:5]
	v_mfma_f32_16x16x32_bf16 v[6:9], v[148:151], v[160:163], v[6:9]
	v_mfma_f32_16x16x32_bf16 v[10:13], v[152:155], v[160:163], v[10:13]
	v_mfma_f32_16x16x32_bf16 v[14:17], v[156:159], v[160:163], v[14:17]
	v_mfma_f32_16x16x32_bf16 v[18:21], v[144:147], v[164:167], v[18:21]
	v_mfma_f32_16x16x32_bf16 v[22:25], v[148:151], v[164:167], v[22:25]
	v_mfma_f32_16x16x32_bf16 v[26:29], v[152:155], v[164:167], v[26:29]
	v_mfma_f32_16x16x32_bf16 v[30:33], v[156:159], v[164:167], v[30:33]
	v_mfma_f32_16x16x32_bf16 v[34:37], v[144:147], v[168:171], v[34:37]
	v_mfma_f32_16x16x32_bf16 v[38:41], v[148:151], v[168:171], v[38:41]
	v_mfma_f32_16x16x32_bf16 v[42:45], v[152:155], v[168:171], v[42:45]
	v_mfma_f32_16x16x32_bf16 v[46:49], v[156:159], v[168:171], v[46:49]
	v_mfma_f32_16x16x32_bf16 v[50:53], v[144:147], v[172:175], v[50:53]
	v_mfma_f32_16x16x32_bf16 v[54:57], v[148:151], v[172:175], v[54:57]
	v_mfma_f32_16x16x32_bf16 v[58:61], v[152:155], v[172:175], v[58:61]
	v_mfma_f32_16x16x32_bf16 v[62:65], v[156:159], v[172:175], v[62:65]
.Lgm_mrg:
	v_pk_add_f32 v[2:3], v[2:3], v[240:241]
	v_pk_add_f32 v[4:5], v[4:5], v[242:243]
	v_mul_f32_e32 v2, 0xbfb8aa3b, v2
	v_mul_f32_e32 v3, 0xbfb8aa3b, v3
	v_mul_f32_e32 v4, 0xbfb8aa3b, v4
	v_mul_f32_e32 v5, 0xbfb8aa3b, v5
	v_exp_f32_e32 v2, v2
	v_exp_f32_e32 v3, v3
	v_exp_f32_e32 v4, v4
	v_exp_f32_e32 v5, v5
	v_lshlrev_b32_e32 v144, 16, v196
	v_and_b32_e32 v145, 0xffff0000, v196
	v_lshlrev_b32_e32 v146, 16, v197
	v_and_b32_e32 v147, 0xffff0000, v197
	v_add_f32_e32 v2, 1.0, v2
	v_add_f32_e32 v3, 1.0, v3
	v_add_f32_e32 v4, 1.0, v4
	v_add_f32_e32 v5, 1.0, v5
	v_rcp_f32_e32 v2, v2
	v_rcp_f32_e32 v3, v3
	v_rcp_f32_e32 v4, v4
	v_rcp_f32_e32 v5, v5
	v_lshlrev_b32_e32 v148, 16, v66
	v_and_b32_e32 v149, 0xffff0000, v66
	v_lshlrev_b32_e32 v150, 16, v67
	v_and_b32_e32 v151, 0xffff0000, v67
	v_fmac_f32_e32 v148, v2, v144
	v_fmac_f32_e32 v149, v3, v145
	v_fmac_f32_e32 v150, v4, v146
	v_fmac_f32_e32 v151, v5, v147
	v_cvt_pk_bf16_f32 v66, v148, v149
	v_cvt_pk_bf16_f32 v67, v150, v151
	v_pk_add_f32 v[6:7], v[6:7], v[244:245]
	v_pk_add_f32 v[8:9], v[8:9], v[246:247]
	v_mul_f32_e32 v6, 0xbfb8aa3b, v6
	v_mul_f32_e32 v7, 0xbfb8aa3b, v7
	v_mul_f32_e32 v8, 0xbfb8aa3b, v8
	v_mul_f32_e32 v9, 0xbfb8aa3b, v9
	v_exp_f32_e32 v6, v6
	v_exp_f32_e32 v7, v7
	v_exp_f32_e32 v8, v8
	v_exp_f32_e32 v9, v9
	v_lshlrev_b32_e32 v160, 16, v198
	v_and_b32_e32 v161, 0xffff0000, v198
	v_lshlrev_b32_e32 v162, 16, v199
	v_and_b32_e32 v163, 0xffff0000, v199
	v_add_f32_e32 v6, 1.0, v6
	v_add_f32_e32 v7, 1.0, v7
	v_add_f32_e32 v8, 1.0, v8
	v_add_f32_e32 v9, 1.0, v9
	v_rcp_f32_e32 v6, v6
	v_rcp_f32_e32 v7, v7
	v_rcp_f32_e32 v8, v8
	v_rcp_f32_e32 v9, v9
	v_lshlrev_b32_e32 v164, 16, v68
	v_and_b32_e32 v165, 0xffff0000, v68
	v_lshlrev_b32_e32 v166, 16, v69
	v_and_b32_e32 v167, 0xffff0000, v69
	v_fmac_f32_e32 v164, v6, v160
	v_fmac_f32_e32 v165, v7, v161
	v_fmac_f32_e32 v166, v8, v162
	v_fmac_f32_e32 v167, v9, v163
	v_cvt_pk_bf16_f32 v68, v164, v165
	v_cvt_pk_bf16_f32 v69, v166, v167
	v_pk_add_f32 v[10:11], v[10:11], v[248:249]
	v_pk_add_f32 v[12:13], v[12:13], v[250:251]
	v_mul_f32_e32 v10, 0xbfb8aa3b, v10
	v_mul_f32_e32 v11, 0xbfb8aa3b, v11
	v_mul_f32_e32 v12, 0xbfb8aa3b, v12
	v_mul_f32_e32 v13, 0xbfb8aa3b, v13
	v_exp_f32_e32 v10, v10
	v_exp_f32_e32 v11, v11
	v_exp_f32_e32 v12, v12
	v_exp_f32_e32 v13, v13
	v_lshlrev_b32_e32 v144, 16, v200
	v_and_b32_e32 v145, 0xffff0000, v200
	v_lshlrev_b32_e32 v146, 16, v201
	v_and_b32_e32 v147, 0xffff0000, v201
	v_add_f32_e32 v10, 1.0, v10
	v_add_f32_e32 v11, 1.0, v11
	v_add_f32_e32 v12, 1.0, v12
	v_add_f32_e32 v13, 1.0, v13
	v_rcp_f32_e32 v10, v10
	v_rcp_f32_e32 v11, v11
	v_rcp_f32_e32 v12, v12
	v_rcp_f32_e32 v13, v13
	v_lshlrev_b32_e32 v148, 16, v70
	v_and_b32_e32 v149, 0xffff0000, v70
	v_lshlrev_b32_e32 v150, 16, v71
	v_and_b32_e32 v151, 0xffff0000, v71
	v_fmac_f32_e32 v148, v10, v144
	v_fmac_f32_e32 v149, v11, v145
	v_fmac_f32_e32 v150, v12, v146
	v_fmac_f32_e32 v151, v13, v147
	v_cvt_pk_bf16_f32 v70, v148, v149
	v_cvt_pk_bf16_f32 v71, v150, v151
	v_pk_add_f32 v[14:15], v[14:15], v[252:253]
	v_pk_add_f32 v[16:17], v[16:17], v[254:255]
	v_mul_f32_e32 v14, 0xbfb8aa3b, v14
	v_mul_f32_e32 v15, 0xbfb8aa3b, v15
	v_mul_f32_e32 v16, 0xbfb8aa3b, v16
	v_mul_f32_e32 v17, 0xbfb8aa3b, v17
	v_exp_f32_e32 v14, v14
	v_exp_f32_e32 v15, v15
	v_exp_f32_e32 v16, v16
	v_exp_f32_e32 v17, v17
	v_lshlrev_b32_e32 v160, 16, v202
	v_and_b32_e32 v161, 0xffff0000, v202
	v_lshlrev_b32_e32 v162, 16, v203
	v_and_b32_e32 v163, 0xffff0000, v203
	v_add_f32_e32 v14, 1.0, v14
	v_add_f32_e32 v15, 1.0, v15
	v_add_f32_e32 v16, 1.0, v16
	v_add_f32_e32 v17, 1.0, v17
	v_rcp_f32_e32 v14, v14
	v_rcp_f32_e32 v15, v15
	v_rcp_f32_e32 v16, v16
	v_rcp_f32_e32 v17, v17
	v_lshlrev_b32_e32 v164, 16, v72
	v_and_b32_e32 v165, 0xffff0000, v72
	v_lshlrev_b32_e32 v166, 16, v73
	v_and_b32_e32 v167, 0xffff0000, v73
	v_fmac_f32_e32 v164, v14, v160
	v_fmac_f32_e32 v165, v15, v161
	v_fmac_f32_e32 v166, v16, v162
	v_fmac_f32_e32 v167, v17, v163
	v_cvt_pk_bf16_f32 v72, v164, v165
	v_cvt_pk_bf16_f32 v73, v166, v167
	v_pk_add_f32 v[18:19], v[18:19], v[240:241]
	v_pk_add_f32 v[20:21], v[20:21], v[242:243]
	v_mul_f32_e32 v18, 0xbfb8aa3b, v18
	v_mul_f32_e32 v19, 0xbfb8aa3b, v19
	v_mul_f32_e32 v20, 0xbfb8aa3b, v20
	v_mul_f32_e32 v21, 0xbfb8aa3b, v21
	v_exp_f32_e32 v18, v18
	v_exp_f32_e32 v19, v19
	v_exp_f32_e32 v20, v20
	v_exp_f32_e32 v21, v21
	v_lshlrev_b32_e32 v144, 16, v204
	v_and_b32_e32 v145, 0xffff0000, v204
	v_lshlrev_b32_e32 v146, 16, v205
	v_and_b32_e32 v147, 0xffff0000, v205
	v_add_f32_e32 v18, 1.0, v18
	v_add_f32_e32 v19, 1.0, v19
	v_add_f32_e32 v20, 1.0, v20
	v_add_f32_e32 v21, 1.0, v21
	v_rcp_f32_e32 v18, v18
	v_rcp_f32_e32 v19, v19
	v_rcp_f32_e32 v20, v20
	v_rcp_f32_e32 v21, v21
	v_lshlrev_b32_e32 v148, 16, v74
	v_and_b32_e32 v149, 0xffff0000, v74
	v_lshlrev_b32_e32 v150, 16, v75
	v_and_b32_e32 v151, 0xffff0000, v75
	v_fmac_f32_e32 v148, v18, v144
	v_fmac_f32_e32 v149, v19, v145
	v_fmac_f32_e32 v150, v20, v146
	v_fmac_f32_e32 v151, v21, v147
	v_cvt_pk_bf16_f32 v74, v148, v149
	v_cvt_pk_bf16_f32 v75, v150, v151
	v_pk_add_f32 v[22:23], v[22:23], v[244:245]
	v_pk_add_f32 v[24:25], v[24:25], v[246:247]
	v_mul_f32_e32 v22, 0xbfb8aa3b, v22
	v_mul_f32_e32 v23, 0xbfb8aa3b, v23
	v_mul_f32_e32 v24, 0xbfb8aa3b, v24
	v_mul_f32_e32 v25, 0xbfb8aa3b, v25
	v_exp_f32_e32 v22, v22
	v_exp_f32_e32 v23, v23
	v_exp_f32_e32 v24, v24
	v_exp_f32_e32 v25, v25
	v_lshlrev_b32_e32 v160, 16, v206
	v_and_b32_e32 v161, 0xffff0000, v206
	v_lshlrev_b32_e32 v162, 16, v207
	v_and_b32_e32 v163, 0xffff0000, v207
	v_add_f32_e32 v22, 1.0, v22
	v_add_f32_e32 v23, 1.0, v23
	v_add_f32_e32 v24, 1.0, v24
	v_add_f32_e32 v25, 1.0, v25
	v_rcp_f32_e32 v22, v22
	v_rcp_f32_e32 v23, v23
	v_rcp_f32_e32 v24, v24
	v_rcp_f32_e32 v25, v25
	v_lshlrev_b32_e32 v164, 16, v76
	v_and_b32_e32 v165, 0xffff0000, v76
	v_lshlrev_b32_e32 v166, 16, v77
	v_and_b32_e32 v167, 0xffff0000, v77
	v_fmac_f32_e32 v164, v22, v160
	v_fmac_f32_e32 v165, v23, v161
	v_fmac_f32_e32 v166, v24, v162
	v_fmac_f32_e32 v167, v25, v163
	v_cvt_pk_bf16_f32 v76, v164, v165
	v_cvt_pk_bf16_f32 v77, v166, v167
	v_pk_add_f32 v[26:27], v[26:27], v[248:249]
	v_pk_add_f32 v[28:29], v[28:29], v[250:251]
	v_mul_f32_e32 v26, 0xbfb8aa3b, v26
	v_mul_f32_e32 v27, 0xbfb8aa3b, v27
	v_mul_f32_e32 v28, 0xbfb8aa3b, v28
	v_mul_f32_e32 v29, 0xbfb8aa3b, v29
	v_exp_f32_e32 v26, v26
	v_exp_f32_e32 v27, v27
	v_exp_f32_e32 v28, v28
	v_exp_f32_e32 v29, v29
	v_lshlrev_b32_e32 v144, 16, v212
	v_and_b32_e32 v145, 0xffff0000, v212
	v_lshlrev_b32_e32 v146, 16, v213
	v_and_b32_e32 v147, 0xffff0000, v213
	v_add_f32_e32 v26, 1.0, v26
	v_add_f32_e32 v27, 1.0, v27
	v_add_f32_e32 v28, 1.0, v28
	v_add_f32_e32 v29, 1.0, v29
	v_rcp_f32_e32 v26, v26
	v_rcp_f32_e32 v27, v27
	v_rcp_f32_e32 v28, v28
	v_rcp_f32_e32 v29, v29
	v_lshlrev_b32_e32 v148, 16, v78
	v_and_b32_e32 v149, 0xffff0000, v78
	v_lshlrev_b32_e32 v150, 16, v79
	v_and_b32_e32 v151, 0xffff0000, v79
	v_fmac_f32_e32 v148, v26, v144
	v_fmac_f32_e32 v149, v27, v145
	v_fmac_f32_e32 v150, v28, v146
	v_fmac_f32_e32 v151, v29, v147
	v_cvt_pk_bf16_f32 v78, v148, v149
	v_cvt_pk_bf16_f32 v79, v150, v151
	v_pk_add_f32 v[30:31], v[30:31], v[252:253]
	v_pk_add_f32 v[32:33], v[32:33], v[254:255]
	v_mul_f32_e32 v30, 0xbfb8aa3b, v30
	v_mul_f32_e32 v31, 0xbfb8aa3b, v31
	v_mul_f32_e32 v32, 0xbfb8aa3b, v32
	v_mul_f32_e32 v33, 0xbfb8aa3b, v33
	v_exp_f32_e32 v30, v30
	v_exp_f32_e32 v31, v31
	v_exp_f32_e32 v32, v32
	v_exp_f32_e32 v33, v33
	v_lshlrev_b32_e32 v160, 16, v214
	v_and_b32_e32 v161, 0xffff0000, v214
	v_lshlrev_b32_e32 v162, 16, v215
	v_and_b32_e32 v163, 0xffff0000, v215
	v_add_f32_e32 v30, 1.0, v30
	v_add_f32_e32 v31, 1.0, v31
	v_add_f32_e32 v32, 1.0, v32
	v_add_f32_e32 v33, 1.0, v33
	v_rcp_f32_e32 v30, v30
	v_rcp_f32_e32 v31, v31
	v_rcp_f32_e32 v32, v32
	v_rcp_f32_e32 v33, v33
	v_lshlrev_b32_e32 v164, 16, v80
	v_and_b32_e32 v165, 0xffff0000, v80
	v_lshlrev_b32_e32 v166, 16, v81
	v_and_b32_e32 v167, 0xffff0000, v81
	v_fmac_f32_e32 v164, v30, v160
	v_fmac_f32_e32 v165, v31, v161
	v_fmac_f32_e32 v166, v32, v162
	v_fmac_f32_e32 v167, v33, v163
	v_cvt_pk_bf16_f32 v80, v164, v165
	v_cvt_pk_bf16_f32 v81, v166, v167
	v_pk_add_f32 v[34:35], v[34:35], v[240:241]
	v_pk_add_f32 v[36:37], v[36:37], v[242:243]
	v_mul_f32_e32 v34, 0xbfb8aa3b, v34
	v_mul_f32_e32 v35, 0xbfb8aa3b, v35
	v_mul_f32_e32 v36, 0xbfb8aa3b, v36
	v_mul_f32_e32 v37, 0xbfb8aa3b, v37
	v_exp_f32_e32 v34, v34
	v_exp_f32_e32 v35, v35
	v_exp_f32_e32 v36, v36
	v_exp_f32_e32 v37, v37
	v_lshlrev_b32_e32 v144, 16, v216
	v_and_b32_e32 v145, 0xffff0000, v216
	v_lshlrev_b32_e32 v146, 16, v217
	v_and_b32_e32 v147, 0xffff0000, v217
	v_add_f32_e32 v34, 1.0, v34
	v_add_f32_e32 v35, 1.0, v35
	v_add_f32_e32 v36, 1.0, v36
	v_add_f32_e32 v37, 1.0, v37
	v_rcp_f32_e32 v34, v34
	v_rcp_f32_e32 v35, v35
	v_rcp_f32_e32 v36, v36
	v_rcp_f32_e32 v37, v37
	v_lshlrev_b32_e32 v148, 16, v82
	v_and_b32_e32 v149, 0xffff0000, v82
	v_lshlrev_b32_e32 v150, 16, v83
	v_and_b32_e32 v151, 0xffff0000, v83
	v_fmac_f32_e32 v148, v34, v144
	v_fmac_f32_e32 v149, v35, v145
	v_fmac_f32_e32 v150, v36, v146
	v_fmac_f32_e32 v151, v37, v147
	v_cvt_pk_bf16_f32 v82, v148, v149
	v_cvt_pk_bf16_f32 v83, v150, v151
	v_pk_add_f32 v[38:39], v[38:39], v[244:245]
	v_pk_add_f32 v[40:41], v[40:41], v[246:247]
	v_mul_f32_e32 v38, 0xbfb8aa3b, v38
	v_mul_f32_e32 v39, 0xbfb8aa3b, v39
	v_mul_f32_e32 v40, 0xbfb8aa3b, v40
	v_mul_f32_e32 v41, 0xbfb8aa3b, v41
	v_exp_f32_e32 v38, v38
	v_exp_f32_e32 v39, v39
	v_exp_f32_e32 v40, v40
	v_exp_f32_e32 v41, v41
	v_lshlrev_b32_e32 v160, 16, v218
	v_and_b32_e32 v161, 0xffff0000, v218
	v_lshlrev_b32_e32 v162, 16, v219
	v_and_b32_e32 v163, 0xffff0000, v219
	v_add_f32_e32 v38, 1.0, v38
	v_add_f32_e32 v39, 1.0, v39
	v_add_f32_e32 v40, 1.0, v40
	v_add_f32_e32 v41, 1.0, v41
	v_rcp_f32_e32 v38, v38
	v_rcp_f32_e32 v39, v39
	v_rcp_f32_e32 v40, v40
	v_rcp_f32_e32 v41, v41
	v_lshlrev_b32_e32 v164, 16, v84
	v_and_b32_e32 v165, 0xffff0000, v84
	v_lshlrev_b32_e32 v166, 16, v85
	v_and_b32_e32 v167, 0xffff0000, v85
	v_fmac_f32_e32 v164, v38, v160
	v_fmac_f32_e32 v165, v39, v161
	v_fmac_f32_e32 v166, v40, v162
	v_fmac_f32_e32 v167, v41, v163
	v_cvt_pk_bf16_f32 v84, v164, v165
	v_cvt_pk_bf16_f32 v85, v166, v167
	v_pk_add_f32 v[42:43], v[42:43], v[248:249]
	v_pk_add_f32 v[44:45], v[44:45], v[250:251]
	v_mul_f32_e32 v42, 0xbfb8aa3b, v42
	v_mul_f32_e32 v43, 0xbfb8aa3b, v43
	v_mul_f32_e32 v44, 0xbfb8aa3b, v44
	v_mul_f32_e32 v45, 0xbfb8aa3b, v45
	v_exp_f32_e32 v42, v42
	v_exp_f32_e32 v43, v43
	v_exp_f32_e32 v44, v44
	v_exp_f32_e32 v45, v45
	v_lshlrev_b32_e32 v144, 16, v220
	v_and_b32_e32 v145, 0xffff0000, v220
	v_lshlrev_b32_e32 v146, 16, v221
	v_and_b32_e32 v147, 0xffff0000, v221
	v_add_f32_e32 v42, 1.0, v42
	v_add_f32_e32 v43, 1.0, v43
	v_add_f32_e32 v44, 1.0, v44
	v_add_f32_e32 v45, 1.0, v45
	v_rcp_f32_e32 v42, v42
	v_rcp_f32_e32 v43, v43
	v_rcp_f32_e32 v44, v44
	v_rcp_f32_e32 v45, v45
	v_lshlrev_b32_e32 v148, 16, v86
	v_and_b32_e32 v149, 0xffff0000, v86
	v_lshlrev_b32_e32 v150, 16, v87
	v_and_b32_e32 v151, 0xffff0000, v87
	v_fmac_f32_e32 v148, v42, v144
	v_fmac_f32_e32 v149, v43, v145
	v_fmac_f32_e32 v150, v44, v146
	v_fmac_f32_e32 v151, v45, v147
	v_cvt_pk_bf16_f32 v86, v148, v149
	v_cvt_pk_bf16_f32 v87, v150, v151
	v_pk_add_f32 v[46:47], v[46:47], v[252:253]
	v_pk_add_f32 v[48:49], v[48:49], v[254:255]
	v_mul_f32_e32 v46, 0xbfb8aa3b, v46
	v_mul_f32_e32 v47, 0xbfb8aa3b, v47
	v_mul_f32_e32 v48, 0xbfb8aa3b, v48
	v_mul_f32_e32 v49, 0xbfb8aa3b, v49
	v_exp_f32_e32 v46, v46
	v_exp_f32_e32 v47, v47
	v_exp_f32_e32 v48, v48
	v_exp_f32_e32 v49, v49
	v_lshlrev_b32_e32 v160, 16, v222
	v_and_b32_e32 v161, 0xffff0000, v222
	v_lshlrev_b32_e32 v162, 16, v223
	v_and_b32_e32 v163, 0xffff0000, v223
	v_add_f32_e32 v46, 1.0, v46
	v_add_f32_e32 v47, 1.0, v47
	v_add_f32_e32 v48, 1.0, v48
	v_add_f32_e32 v49, 1.0, v49
	v_rcp_f32_e32 v46, v46
	v_rcp_f32_e32 v47, v47
	v_rcp_f32_e32 v48, v48
	v_rcp_f32_e32 v49, v49
	v_lshlrev_b32_e32 v164, 16, v88
	v_and_b32_e32 v165, 0xffff0000, v88
	v_lshlrev_b32_e32 v166, 16, v89
	v_and_b32_e32 v167, 0xffff0000, v89
	v_fmac_f32_e32 v164, v46, v160
	v_fmac_f32_e32 v165, v47, v161
	v_fmac_f32_e32 v166, v48, v162
	v_fmac_f32_e32 v167, v49, v163
	v_cvt_pk_bf16_f32 v88, v164, v165
	v_cvt_pk_bf16_f32 v89, v166, v167
	v_pk_add_f32 v[50:51], v[50:51], v[240:241]
	v_pk_add_f32 v[52:53], v[52:53], v[242:243]
	v_mul_f32_e32 v50, 0xbfb8aa3b, v50
	v_mul_f32_e32 v51, 0xbfb8aa3b, v51
	v_mul_f32_e32 v52, 0xbfb8aa3b, v52
	v_mul_f32_e32 v53, 0xbfb8aa3b, v53
	v_exp_f32_e32 v50, v50
	v_exp_f32_e32 v51, v51
	v_exp_f32_e32 v52, v52
	v_exp_f32_e32 v53, v53
	v_lshlrev_b32_e32 v144, 16, v224
	v_and_b32_e32 v145, 0xffff0000, v224
	v_lshlrev_b32_e32 v146, 16, v225
	v_and_b32_e32 v147, 0xffff0000, v225
	v_add_f32_e32 v50, 1.0, v50
	v_add_f32_e32 v51, 1.0, v51
	v_add_f32_e32 v52, 1.0, v52
	v_add_f32_e32 v53, 1.0, v53
	v_rcp_f32_e32 v50, v50
	v_rcp_f32_e32 v51, v51
	v_rcp_f32_e32 v52, v52
	v_rcp_f32_e32 v53, v53
	v_lshlrev_b32_e32 v148, 16, v122
	v_and_b32_e32 v149, 0xffff0000, v122
	v_lshlrev_b32_e32 v150, 16, v123
	v_and_b32_e32 v151, 0xffff0000, v123
	v_fmac_f32_e32 v148, v50, v144
	v_fmac_f32_e32 v149, v51, v145
	v_fmac_f32_e32 v150, v52, v146
	v_fmac_f32_e32 v151, v53, v147
	v_cvt_pk_bf16_f32 v122, v148, v149
	v_cvt_pk_bf16_f32 v123, v150, v151
	v_pk_add_f32 v[54:55], v[54:55], v[244:245]
	v_pk_add_f32 v[56:57], v[56:57], v[246:247]
	v_mul_f32_e32 v54, 0xbfb8aa3b, v54
	v_mul_f32_e32 v55, 0xbfb8aa3b, v55
	v_mul_f32_e32 v56, 0xbfb8aa3b, v56
	v_mul_f32_e32 v57, 0xbfb8aa3b, v57
	v_exp_f32_e32 v54, v54
	v_exp_f32_e32 v55, v55
	v_exp_f32_e32 v56, v56
	v_exp_f32_e32 v57, v57
	v_lshlrev_b32_e32 v160, 16, v226
	v_and_b32_e32 v161, 0xffff0000, v226
	v_lshlrev_b32_e32 v162, 16, v227
	v_and_b32_e32 v163, 0xffff0000, v227
	v_add_f32_e32 v54, 1.0, v54
	v_add_f32_e32 v55, 1.0, v55
	v_add_f32_e32 v56, 1.0, v56
	v_add_f32_e32 v57, 1.0, v57
	v_rcp_f32_e32 v54, v54
	v_rcp_f32_e32 v55, v55
	v_rcp_f32_e32 v56, v56
	v_rcp_f32_e32 v57, v57
	v_lshlrev_b32_e32 v164, 16, v124
	v_and_b32_e32 v165, 0xffff0000, v124
	v_lshlrev_b32_e32 v166, 16, v125
	v_and_b32_e32 v167, 0xffff0000, v125
	v_fmac_f32_e32 v164, v54, v160
	v_fmac_f32_e32 v165, v55, v161
	v_fmac_f32_e32 v166, v56, v162
	v_fmac_f32_e32 v167, v57, v163
	v_cvt_pk_bf16_f32 v124, v164, v165
	v_cvt_pk_bf16_f32 v125, v166, v167
	v_pk_add_f32 v[58:59], v[58:59], v[248:249]
	v_pk_add_f32 v[60:61], v[60:61], v[250:251]
	v_mul_f32_e32 v58, 0xbfb8aa3b, v58
	v_mul_f32_e32 v59, 0xbfb8aa3b, v59
	v_mul_f32_e32 v60, 0xbfb8aa3b, v60
	v_mul_f32_e32 v61, 0xbfb8aa3b, v61
	v_exp_f32_e32 v58, v58
	v_exp_f32_e32 v59, v59
	v_exp_f32_e32 v60, v60
	v_exp_f32_e32 v61, v61
	v_lshlrev_b32_e32 v144, 16, v228
	v_and_b32_e32 v145, 0xffff0000, v228
	v_lshlrev_b32_e32 v146, 16, v229
	v_and_b32_e32 v147, 0xffff0000, v229
	v_add_f32_e32 v58, 1.0, v58
	v_add_f32_e32 v59, 1.0, v59
	v_add_f32_e32 v60, 1.0, v60
	v_add_f32_e32 v61, 1.0, v61
	v_rcp_f32_e32 v58, v58
	v_rcp_f32_e32 v59, v59
	v_rcp_f32_e32 v60, v60
	v_rcp_f32_e32 v61, v61
	v_lshlrev_b32_e32 v148, 16, v126
	v_and_b32_e32 v149, 0xffff0000, v126
	v_lshlrev_b32_e32 v150, 16, v127
	v_and_b32_e32 v151, 0xffff0000, v127
	v_fmac_f32_e32 v148, v58, v144
	v_fmac_f32_e32 v149, v59, v145
	v_fmac_f32_e32 v150, v60, v146
	v_fmac_f32_e32 v151, v61, v147
	v_cvt_pk_bf16_f32 v126, v148, v149
	v_cvt_pk_bf16_f32 v127, v150, v151
	v_pk_add_f32 v[62:63], v[62:63], v[252:253]
	v_pk_add_f32 v[64:65], v[64:65], v[254:255]
	v_mul_f32_e32 v62, 0xbfb8aa3b, v62
	v_mul_f32_e32 v63, 0xbfb8aa3b, v63
	v_mul_f32_e32 v64, 0xbfb8aa3b, v64
	v_mul_f32_e32 v65, 0xbfb8aa3b, v65
	v_exp_f32_e32 v62, v62
	v_exp_f32_e32 v63, v63
	v_exp_f32_e32 v64, v64
	v_exp_f32_e32 v65, v65
	v_lshlrev_b32_e32 v160, 16, v230
	v_and_b32_e32 v161, 0xffff0000, v230
	v_lshlrev_b32_e32 v162, 16, v231
	v_and_b32_e32 v163, 0xffff0000, v231
	v_add_f32_e32 v62, 1.0, v62
	v_add_f32_e32 v63, 1.0, v63
	v_add_f32_e32 v64, 1.0, v64
	v_add_f32_e32 v65, 1.0, v65
	v_rcp_f32_e32 v62, v62
	v_rcp_f32_e32 v63, v63
	v_rcp_f32_e32 v64, v64
	v_rcp_f32_e32 v65, v65
	v_lshlrev_b32_e32 v164, 16, v128
	v_and_b32_e32 v165, 0xffff0000, v128
	v_lshlrev_b32_e32 v166, 16, v129
	v_and_b32_e32 v167, 0xffff0000, v129
	v_fmac_f32_e32 v164, v62, v160
	v_fmac_f32_e32 v165, v63, v161
	v_fmac_f32_e32 v166, v64, v162
	v_fmac_f32_e32 v167, v65, v163
	v_cvt_pk_bf16_f32 v128, v164, v165
	v_cvt_pk_bf16_f32 v129, v166, v167
	s_add_u32 s26, s26, 1
	s_cmp_lt_u32 s26, 4
	s_cbranch_scc1 .Lgm_branch
	global_store_dwordx2 v143, v[66:67], s[10:11]
	global_store_dwordx2 v143, v[68:69], s[10:11] offset:32
	global_store_dwordx2 v143, v[70:71], s[10:11] offset:64
	global_store_dwordx2 v143, v[72:73], s[10:11] offset:96
	v_add_u32_e32 v131, 0x8000, v143
	global_store_dwordx2 v131, v[74:75], s[10:11]
	global_store_dwordx2 v131, v[76:77], s[10:11] offset:32
	global_store_dwordx2 v131, v[78:79], s[10:11] offset:64
	global_store_dwordx2 v131, v[80:81], s[10:11] offset:96
	v_add_u32_e32 v131, 0x10000, v143
	global_store_dwordx2 v131, v[82:83], s[10:11]
	global_store_dwordx2 v131, v[84:85], s[10:11] offset:32
	global_store_dwordx2 v131, v[86:87], s[10:11] offset:64
	global_store_dwordx2 v131, v[88:89], s[10:11] offset:96
	v_add_u32_e32 v131, 0x18000, v143
	global_store_dwordx2 v131, v[122:123], s[10:11]
	global_store_dwordx2 v131, v[124:125], s[10:11] offset:32
	global_store_dwordx2 v131, v[126:127], s[10:11] offset:64
	global_store_dwordx2 v131, v[128:129], s[10:11] offset:96
	s_cmp_lg_u32 s27, 0
	s_cbranch_scc1 .Lgm_tile
.Lgm_done:
	s_branch .LBB0_90
.LBB0_89:
	v_readlane_b32 s34, v239, 28
	v_readlane_b32 s36, v239, 30
	s_mov_b64 s[30:31], s[40:41]
	s_movk_i32 s41, 0x1000
	v_readlane_b32 s35, v239, 29
	v_readlane_b32 s37, v239, 31
	v_readlane_b32 s38, v239, 33
	v_readlane_b32 s39, v239, 34
	s_movk_i32 s40, 0x2000
	s_movk_i32 s44, 0x3000
	s_movk_i32 s45, 0x6000
	s_movk_i32 s46, 0x1800
	s_movk_i32 s47, 0x1fff

	.amdhsa_kernel _Z2mk6Paramsii
		.amdhsa_group_segment_fixed_size 0
		.amdhsa_private_segment_fixed_size 0
		.amdhsa_kernarg_size 576
		.amdhsa_user_sgpr_count 2
		.amdhsa_user_sgpr_dispatch_ptr 0
		.amdhsa_user_sgpr_queue_ptr 0
		.amdhsa_user_sgpr_kernarg_segment_ptr 1
		.amdhsa_user_sgpr_dispatch_id 0
		.amdhsa_user_sgpr_kernarg_preload_length 0
		.amdhsa_user_sgpr_kernarg_preload_offset 0
		.amdhsa_user_sgpr_private_segment_size 0
		.amdhsa_uses_dynamic_stack 0
		.amdhsa_enable_private_segment 0
		.amdhsa_system_sgpr_workgroup_id_x 1
		.amdhsa_system_sgpr_workgroup_id_y 0
		.amdhsa_system_sgpr_workgroup_id_z 0
		.amdhsa_system_sgpr_workgroup_info 0
		.amdhsa_system_vgpr_workitem_id 2
		.amdhsa_next_free_vgpr 256
		.amdhsa_next_free_sgpr 100
		.amdhsa_accum_offset 256
		.amdhsa_reserve_vcc 1
		.amdhsa_float_round_mode_32 0
		.amdhsa_float_round_mode_16_64 0
		.amdhsa_float_denorm_mode_32 3
		.amdhsa_float_denorm_mode_16_64 3
		.amdhsa_dx10_clamp 1
		.amdhsa_ieee_mode 1
		.amdhsa_fp16_overflow 0
		.amdhsa_tg_split 0
		.amdhsa_exception_fp_ieee_invalid_op 0
		.amdhsa_exception_fp_denorm_src 0
		.amdhsa_exception_fp_ieee_div_zero 0
		.amdhsa_exception_fp_ieee_overflow 0
		.amdhsa_exception_fp_ieee_underflow 0
		.amdhsa_exception_fp_ieee_inexact 0
		.amdhsa_exception_int_div_zero 0
	.end_amdhsa_kernel

amdhsa.kernels:
  - .agpr_count:     0
    .args:
      - .offset:         0
        .size:           312
        .value_kind:     by_value
      - .offset:         312
        .size:           4
        .value_kind:     by_value
      - .offset:         316
        .size:           4
        .value_kind:     by_value
      - .offset:         320
        .size:           4
        .value_kind:     hidden_block_count_x
      - .offset:         324
        .size:           4
        .value_kind:     hidden_block_count_y
      - .offset:         328
        .size:           4
        .value_kind:     hidden_block_count_z
      - .offset:         332
        .size:           2
        .value_kind:     hidden_group_size_x
      - .offset:         334
        .size:           2
        .value_kind:     hidden_group_size_y
      - .offset:         336
        .size:           2
        .value_kind:     hidden_group_size_z
      - .offset:         338
        .size:           2
        .value_kind:     hidden_remainder_x
      - .offset:         340
        .size:           2
        .value_kind:     hidden_remainder_y
      - .offset:         342
        .size:           2
        .value_kind:     hidden_remainder_z
      - .offset:         360
        .size:           8
        .value_kind:     hidden_global_offset_x
      - .offset:         368
        .size:           8
        .value_kind:     hidden_global_offset_y
      - .offset:         376
        .size:           8
        .value_kind:     hidden_global_offset_z
      - .offset:         384
        .size:           2
        .value_kind:     hidden_grid_dims
      - .offset:         408
        .size:           8
        .value_kind:     hidden_multigrid_sync_arg
      - .offset:         440
        .size:           4
        .value_kind:     hidden_dynamic_lds_size
    .group_segment_fixed_size: 0
    .kernarg_segment_align: 8
    .kernarg_segment_size: 576
    .language:       OpenCL C
    .language_version:
      - 2
      - 0
    .max_flat_workgroup_size: 256
    .name:           _Z2mk6Paramsii
    .private_segment_fixed_size: 0
    .sgpr_count:     106
    .sgpr_spill_count: 80
    .symbol:         _Z2mk6Paramsii.kd
    .uniform_work_group_size: 1
    .uses_dynamic_stack: false
    .vgpr_count:     256
    .vgpr_spill_count: 0
    .wavefront_size: 64
